# trailing half (waves 4-7) at s_setprio 1 during the GEMM epilogues, reset at the tile-end join; on top of v39
# speedup vs baseline: 1.0033x; 1.0012x over previous
; #define PG8_BAR __builtin_amdgcn_s_barrier()
; template <class Epi, class Sched, bool ALIGN_EPI = false, bool SP2 = false>
; __device__ __forceinline__ void gemm_phase(PG8_LAS unsigned char* lds, const Gemm g, const Sched& S, const Epi& E) {
;     ...
;         if constexpr (!Epi::AFTER_DRAIN) { E(acc, cur, wr, wc, fr, fq, ui, lds); S.done(cur); }
;         if (!has_next) break;
; #pragma unroll
;         for (int a = 0; a < 2; ++a)
; #pragma unroll
;             for (int b = 0; b < 2; ++b)
; #pragma unroll
;                 for (int m = 0; m < 4; ++m)
; #pragma unroll
;                     for (int n = 0; n < 2; ++n) acc[a][b][m][n] = (f32x4){0.f, 0.f, 0.f, 0.f};
;         cur = nxt; cA = nA; cB = nB; ++ui;
;         if constexpr (ALIGN_EPI) { if (wr == 1) PG8_BAR; }
;     }
.LBB0_215:
	s_setprio 0
	s_andn2_b64 vcc, exec, s[0:1]
	s_mov_b32 s0, s70
	s_mov_b32 s78, s72
	s_mov_b64 s[46:47], s[76:77]
	s_mov_b64 s[48:49], s[74:75]
	s_mov_b32 s1, s67
	s_cbranch_vccz .LBB0_1111

; #define PG8_STAGE(bufoff, gbase, voff) do { _Pragma("unroll") for (int _i = 0; _i < 2; ++_i) \
;         __builtin_amdgcn_global_load_lds((const unsigned*)((const char*)(gbase) + (voff)[_i]), (PG8_LAS unsigned*)(lds + (bufoff) + ldsw + _i * 8192), 16, 0, 0); } while (0)
; #define PG8_LDA(dst, b, h) do { _Pragma("unroll") for (int m = 0; m < 4; ++m) _Pragma("unroll") for (int k = 0; k < 2; ++k) dst[m][k] = *(const PG8_LAS bf16x8*)(lds + PG8_SA(b, h) + aoff + m * 2048 + k * 1024); } while (0)
; #define PG8_LDB(dst, b, h) do { _Pragma("unroll") for (int n = 0; n < 2; ++n) _Pragma("unroll") for (int k = 0; k < 2; ++k) dst[n][k] = *(const PG8_LAS bf16x8*)(lds + PG8_SB(b, h) + boff + n * 2048 + k * 1024); } while (0)
; #define PG8_MMA(ai, bj, At, Bt) do { __builtin_amdgcn_s_setprio(1); _Pragma("unroll") for (int m = 0; m < 4; ++m) _Pragma("unroll") for (int n = 0; n < 2; ++n) _Pragma("unroll") for (int k = 0; k < 2; ++k) \
;         acc[ai][bj][m][n] = __builtin_amdgcn_mfma_f32_16x16x32_bf16(Bt[n][k], At[m][k], acc[ai][bj][m][n], 0, 0, 0); __builtin_amdgcn_s_setprio(0); } while (0)
; #define PG8_WAIT_V(n) asm volatile("s_waitcnt vmcnt(" #n ")" ::: "memory")
; #define PG8_WAIT_L(n) asm volatile("s_waitcnt lgkmcnt(" #n ")" ::: "memory")
; #define PG8_BAR __builtin_amdgcn_s_barrier()
; #define PG8_SCHED __builtin_amdgcn_sched_barrier(0)
; template <class Epi, class Sched, bool ALIGN_EPI = false, bool SP2 = false>
; __device__ __forceinline__ void gemm_phase(PG8_LAS unsigned char* lds, const Gemm g, const Sched& S, const Epi& E) {
;     ...
;             PG8_LDB(B0, 0, 0); PG8_LDB(B1, 0, 1); PG8_SCHED; PG8_LDA(At, 0, 0); PG8_STAGE(PG8_SA(1, 1), a1 + hstep, voffA);
;             PG8_WAIT_V(8); PG8_WAIT_L(0); PG8_BAR; PG8_MMA(0, 0, At, B0); PG8_MMA(0, 1, At, B1); PG8_BAR; PG8_SCHED;
;             PG8_LDA(At, 0, 1); PG8_STAGE(PG8_SB(0, 0), b2, voffB); PG8_STAGE(PG8_SB(0, 1), b2 + hstep, voffB); PG8_STAGE(PG8_SA(0, 0), a2, voffA);
.LBB0_219:
	s_add_u32 s46, s38, 0xfffc0080
	s_addc_u32 s47, s39, -1
	s_add_i32 s56, 0, 0x10000
	s_cmp_eq_u32 vcc_lo, 12
	s_cselect_b32 s49, s50, s47
	s_cselect_b32 s48, s51, s46
	s_cselect_b32 s47, s52, s73
	s_cselect_b32 s46, s53, s71
	s_add_i32 vcc_hi, 0, 0x14000
	v_add_u32_e32 v152, s56, v165
	v_add_u32_e32 v169, vcc_hi, v165
	ds_read_b128 v[128:131], v152
	ds_read_b128 v[144:147], v152 offset:1024
	ds_read_b128 v[148:151], v152 offset:2048
	ds_read_b128 v[152:155], v152 offset:3072
	ds_read_b128 v[156:159], v169
	ds_read_b128 v[160:163], v169 offset:1024
	ds_read_b128 v[170:173], v169 offset:2048
	ds_read_b128 v[180:183], v169 offset:3072
	v_lshl_add_u64 v[176:177], s[38:39], 0, v[140:141]
	s_add_i32 m0, s9, 0xc000
	ds_read_b128 v[184:187], v168
	ds_read_b128 v[188:191], v168 offset:1024
	ds_read_b128 v[192:195], v168 offset:2048
	ds_read_b128 v[196:199], v168 offset:3072
	ds_read_b128 v[200:203], v168 offset:4096
	ds_read_b128 v[204:207], v168 offset:5120
	ds_read_b128 v[218:221], v168 offset:6144
	ds_read_b128 v[222:225], v168 offset:7168
	global_load_lds_dwordx4 v[176:177], off
	v_lshl_add_u64 v[176:177], s[38:39], 0, v[142:143]
	s_add_i32 m0, s9, 0xe000
	s_nop 0
	global_load_lds_dwordx4 v[176:177], off
	s_waitcnt vmcnt(8)
	s_waitcnt lgkmcnt(0)
	s_setprio 1
	s_barrier
	v_mfma_f32_16x16x32_bf16 v[124:127], v[128:131], v[184:187], v[124:127]
	v_mfma_f32_16x16x32_bf16 v[120:123], v[148:151], v[184:187], v[120:123]
	v_mfma_f32_16x16x32_bf16 v[108:111], v[128:131], v[192:195], v[108:111]
	v_mfma_f32_16x16x32_bf16 v[104:107], v[148:151], v[192:195], v[104:107]
	v_mfma_f32_16x16x32_bf16 v[92:95], v[128:131], v[200:203], v[92:95]
	v_mfma_f32_16x16x32_bf16 v[88:91], v[148:151], v[200:203], v[88:91]
	v_mfma_f32_16x16x32_bf16 v[76:79], v[128:131], v[218:221], v[76:79]
	v_mfma_f32_16x16x32_bf16 v[72:75], v[148:151], v[218:221], v[72:75]
	v_mfma_f32_16x16x32_bf16 v[124:127], v[144:147], v[188:191], v[124:127]
	v_mfma_f32_16x16x32_bf16 v[120:123], v[152:155], v[188:191], v[120:123]
	v_mfma_f32_16x16x32_bf16 v[108:111], v[144:147], v[196:199], v[108:111]
	v_mfma_f32_16x16x32_bf16 v[104:107], v[152:155], v[196:199], v[104:107]
	v_mfma_f32_16x16x32_bf16 v[92:95], v[144:147], v[204:207], v[92:95]
	v_mfma_f32_16x16x32_bf16 v[88:91], v[152:155], v[204:207], v[88:91]
	v_mfma_f32_16x16x32_bf16 v[76:79], v[144:147], v[222:225], v[76:79]
	v_mfma_f32_16x16x32_bf16 v[72:75], v[152:155], v[222:225], v[72:75]
	v_mfma_f32_16x16x32_bf16 v[116:119], v[156:159], v[184:187], v[116:119]
	v_mfma_f32_16x16x32_bf16 v[112:115], v[170:173], v[184:187], v[112:115]
	v_mfma_f32_16x16x32_bf16 v[100:103], v[156:159], v[192:195], v[100:103]
	v_mfma_f32_16x16x32_bf16 v[96:99], v[170:173], v[192:195], v[96:99]
	v_mfma_f32_16x16x32_bf16 v[84:87], v[156:159], v[200:203], v[84:87]
	v_mfma_f32_16x16x32_bf16 v[80:83], v[170:173], v[200:203], v[80:83]
	v_mfma_f32_16x16x32_bf16 v[68:71], v[156:159], v[218:221], v[68:71]
	v_mfma_f32_16x16x32_bf16 v[64:67], v[170:173], v[218:221], v[64:67]
	v_mfma_f32_16x16x32_bf16 v[116:119], v[160:163], v[188:191], v[116:119]
	v_mfma_f32_16x16x32_bf16 v[112:115], v[180:183], v[188:191], v[112:115]
	v_mfma_f32_16x16x32_bf16 v[100:103], v[160:163], v[196:199], v[100:103]
	v_mfma_f32_16x16x32_bf16 v[96:99], v[180:183], v[196:199], v[96:99]
	v_mfma_f32_16x16x32_bf16 v[84:87], v[160:163], v[204:207], v[84:87]
	v_mfma_f32_16x16x32_bf16 v[80:83], v[180:183], v[204:207], v[80:83]
	v_mfma_f32_16x16x32_bf16 v[68:71], v[160:163], v[222:225], v[68:71]
	v_mfma_f32_16x16x32_bf16 v[64:67], v[180:183], v[222:225], v[64:67]
	s_barrier
	s_setprio 0
	s_add_i32 s56, s56, s8
	v_lshl_add_u64 v[176:177], s[46:47], 0, v[174:175]
	s_mov_b32 m0, s56
	ds_read_b128 v[184:187], v168 offset:16384
	ds_read_b128 v[188:191], v168 offset:17408
	ds_read_b128 v[192:195], v168 offset:18432
	ds_read_b128 v[196:199], v168 offset:19456
	ds_read_b128 v[200:203], v168 offset:20480
	ds_read_b128 v[204:207], v168 offset:21504
	ds_read_b128 v[218:221], v168 offset:22528
	ds_read_b128 v[222:225], v168 offset:23552
	global_load_lds_dwordx4 v[176:177], off
	s_add_i32 m0, s56, 0x2000
	s_add_u32 s56, s46, 0x40000
	v_lshl_add_u64 v[178:179], s[46:47], 0, v[136:137]
	s_addc_u32 s57, s47, 0
	s_add_i32 vcc_hi, vcc_hi, s8
	global_load_lds_dwordx4 v[178:179], off
	v_lshl_add_u64 v[208:209], s[56:57], 0, v[174:175]
	s_mov_b32 m0, vcc_hi
	v_lshl_add_u64 v[226:227], s[48:49], 0, v[134:135]
	global_load_lds_dwordx4 v[208:209], off
	v_lshl_add_u64 v[208:209], s[56:57], 0, v[136:137]
	s_add_i32 m0, vcc_hi, 0x2000
	s_nop 0
	global_load_lds_dwordx4 v[208:209], off
	v_lshl_add_u64 v[208:209], s[48:49], 0, v[132:133]
	s_mov_b32 m0, s9
	s_nop 0
	global_load_lds_dwordx4 v[208:209], off
	s_mov_b32 m0, s79
	s_nop 0
	global_load_lds_dwordx4 v[226:227], off
	s_waitcnt vmcnt(8)
	s_waitcnt lgkmcnt(0)
	s_setprio 1
	s_barrier
; #define PG8_STAGE(bufoff, gbase, voff) do { _Pragma("unroll") for (int _i = 0; _i < 2; ++_i) \
;         __builtin_amdgcn_global_load_lds((const unsigned*)((const char*)(gbase) + (voff)[_i]), (PG8_LAS unsigned*)(lds + (bufoff) + ldsw + _i * 8192), 16, 0, 0); } while (0)
; #define PG8_LDA(dst, b, h) do { _Pragma("unroll") for (int m = 0; m < 4; ++m) _Pragma("unroll") for (int k = 0; k < 2; ++k) dst[m][k] = *(const PG8_LAS bf16x8*)(lds + PG8_SA(b, h) + aoff + m * 2048 + k * 1024); } while (0)
; #define PG8_LDB(dst, b, h) do { _Pragma("unroll") for (int n = 0; n < 2; ++n) _Pragma("unroll") for (int k = 0; k < 2; ++k) dst[n][k] = *(const PG8_LAS bf16x8*)(lds + PG8_SB(b, h) + boff + n * 2048 + k * 1024); } while (0)
; #define PG8_MMA(ai, bj, At, Bt) do { __builtin_amdgcn_s_setprio(1); _Pragma("unroll") for (int m = 0; m < 4; ++m) _Pragma("unroll") for (int n = 0; n < 2; ++n) _Pragma("unroll") for (int k = 0; k < 2; ++k) \
;         acc[ai][bj][m][n] = __builtin_amdgcn_mfma_f32_16x16x32_bf16(Bt[n][k], At[m][k], acc[ai][bj][m][n], 0, 0, 0); __builtin_amdgcn_s_setprio(0); } while (0)
; #define PG8_WAIT_V(n) asm volatile("s_waitcnt vmcnt(" #n ")" ::: "memory")
; #define PG8_WAIT_L(n) asm volatile("s_waitcnt lgkmcnt(" #n ")" ::: "memory")
; #define PG8_BAR __builtin_amdgcn_s_barrier()
; #define PG8_SCHED __builtin_amdgcn_sched_barrier(0)
; template <class Epi, class Sched, bool ALIGN_EPI = false, bool SP2 = false>
; __device__ __forceinline__ void gemm_phase(PG8_LAS unsigned char* lds, const Gemm g, const Sched& S, const Epi& E) {
;     ...
;             PG8_WAIT_V(8); PG8_WAIT_L(0); PG8_BAR; PG8_MMA(1, 0, At, B0); PG8_MMA(1, 1, At, B1); PG8_BAR; PG8_SCHED;
;             PG8_LDB(B0, 1, 0); PG8_LDB(B1, 1, 1); PG8_SCHED; PG8_LDA(At, 1, 0); PG8_STAGE(PG8_SA(0, 1), a2 + hstep, voffA);
;             PG8_WAIT_V(8); PG8_WAIT_L(0); PG8_BAR; PG8_MMA(0, 0, At, B0); PG8_MMA(0, 1, At, B1); PG8_BAR; PG8_SCHED;
	v_mfma_f32_16x16x32_bf16 v[60:63], v[128:131], v[184:187], v[60:63]
	v_mfma_f32_16x16x32_bf16 v[56:59], v[148:151], v[184:187], v[56:59]
	v_mfma_f32_16x16x32_bf16 v[44:47], v[128:131], v[192:195], v[44:47]
	v_mfma_f32_16x16x32_bf16 v[40:43], v[148:151], v[192:195], v[40:43]
	v_mfma_f32_16x16x32_bf16 v[28:31], v[128:131], v[200:203], v[28:31]
	v_mfma_f32_16x16x32_bf16 v[24:27], v[148:151], v[200:203], v[24:27]
	v_mfma_f32_16x16x32_bf16 v[12:15], v[128:131], v[218:221], v[12:15]
	v_mfma_f32_16x16x32_bf16 v[8:11], v[148:151], v[218:221], v[8:11]
	v_mfma_f32_16x16x32_bf16 v[60:63], v[144:147], v[188:191], v[60:63]
	v_mfma_f32_16x16x32_bf16 v[56:59], v[152:155], v[188:191], v[56:59]
	v_mfma_f32_16x16x32_bf16 v[44:47], v[144:147], v[196:199], v[44:47]
	v_mfma_f32_16x16x32_bf16 v[40:43], v[152:155], v[196:199], v[40:43]
	v_mfma_f32_16x16x32_bf16 v[28:31], v[144:147], v[204:207], v[28:31]
	v_mfma_f32_16x16x32_bf16 v[24:27], v[152:155], v[204:207], v[24:27]
	v_mfma_f32_16x16x32_bf16 v[12:15], v[144:147], v[222:225], v[12:15]
	v_mfma_f32_16x16x32_bf16 v[8:11], v[152:155], v[222:225], v[8:11]
	v_mfma_f32_16x16x32_bf16 v[52:55], v[156:159], v[184:187], v[52:55]
	v_mfma_f32_16x16x32_bf16 v[48:51], v[170:173], v[184:187], v[48:51]
	v_mfma_f32_16x16x32_bf16 v[36:39], v[156:159], v[192:195], v[36:39]
	v_mfma_f32_16x16x32_bf16 v[32:35], v[170:173], v[192:195], v[32:35]
	v_mfma_f32_16x16x32_bf16 v[20:23], v[156:159], v[200:203], v[20:23]
	v_mfma_f32_16x16x32_bf16 v[16:19], v[170:173], v[200:203], v[16:19]
	v_mfma_f32_16x16x32_bf16 v[4:7], v[156:159], v[218:221], v[4:7]
	v_mfma_f32_16x16x32_bf16 v[0:3], v[170:173], v[218:221], v[0:3]
	v_mfma_f32_16x16x32_bf16 v[52:55], v[160:163], v[188:191], v[52:55]
	v_mfma_f32_16x16x32_bf16 v[48:51], v[180:183], v[188:191], v[48:51]
	v_mfma_f32_16x16x32_bf16 v[36:39], v[160:163], v[196:199], v[36:39]
	v_mfma_f32_16x16x32_bf16 v[32:35], v[180:183], v[196:199], v[32:35]
	v_mfma_f32_16x16x32_bf16 v[20:23], v[160:163], v[204:207], v[20:23]
	v_mfma_f32_16x16x32_bf16 v[16:19], v[180:183], v[204:207], v[16:19]
	v_mfma_f32_16x16x32_bf16 v[4:7], v[160:163], v[222:225], v[4:7]
	v_mfma_f32_16x16x32_bf16 v[0:3], v[180:183], v[222:225], v[0:3]
	s_barrier
	s_setprio 0
	s_add_i32 s56, 0, 0x18000
	s_add_i32 s57, 0, 0x1c000
	v_add_u32_e32 v152, s56, v165
	v_add_u32_e32 v169, s57, v165
	ds_read_b128 v[128:131], v152
	ds_read_b128 v[144:147], v152 offset:1024
	ds_read_b128 v[148:151], v152 offset:2048
	ds_read_b128 v[152:155], v152 offset:3072
	ds_read_b128 v[156:159], v169
	ds_read_b128 v[160:163], v169 offset:1024
	ds_read_b128 v[170:173], v169 offset:2048
	ds_read_b128 v[180:183], v169 offset:3072
	s_add_u32 s48, s48, 0x40000
	s_addc_u32 s49, s49, 0
	s_mov_b32 m0, s54
	v_lshl_add_u64 v[228:229], s[48:49], 0, v[132:133]
	ds_read_b128 v[184:187], v168 offset:32768
	ds_read_b128 v[188:191], v168 offset:33792
	ds_read_b128 v[192:195], v168 offset:34816
	ds_read_b128 v[196:199], v168 offset:35840
	ds_read_b128 v[200:203], v168 offset:36864
	ds_read_b128 v[204:207], v168 offset:37888
	ds_read_b128 v[218:221], v168 offset:38912
	ds_read_b128 v[222:225], v168 offset:39936
	global_load_lds_dwordx4 v[228:229], off
	v_lshl_add_u64 v[228:229], s[48:49], 0, v[134:135]
	s_mov_b32 m0, s55
	s_nop 0
	global_load_lds_dwordx4 v[228:229], off
	s_waitcnt vmcnt(8)
	s_waitcnt lgkmcnt(0)
	s_setprio 1
	s_barrier
	v_mfma_f32_16x16x32_bf16 v[124:127], v[128:131], v[184:187], v[124:127]
	v_mfma_f32_16x16x32_bf16 v[120:123], v[148:151], v[184:187], v[120:123]
	v_mfma_f32_16x16x32_bf16 v[108:111], v[128:131], v[192:195], v[108:111]
	v_mfma_f32_16x16x32_bf16 v[104:107], v[148:151], v[192:195], v[104:107]
	v_mfma_f32_16x16x32_bf16 v[92:95], v[128:131], v[200:203], v[92:95]
	v_mfma_f32_16x16x32_bf16 v[88:91], v[148:151], v[200:203], v[88:91]
	v_mfma_f32_16x16x32_bf16 v[76:79], v[128:131], v[218:221], v[76:79]
	v_mfma_f32_16x16x32_bf16 v[72:75], v[148:151], v[218:221], v[72:75]
	v_mfma_f32_16x16x32_bf16 v[124:127], v[144:147], v[188:191], v[124:127]
	v_mfma_f32_16x16x32_bf16 v[120:123], v[152:155], v[188:191], v[120:123]
	v_mfma_f32_16x16x32_bf16 v[108:111], v[144:147], v[196:199], v[108:111]
	v_mfma_f32_16x16x32_bf16 v[104:107], v[152:155], v[196:199], v[104:107]
	v_mfma_f32_16x16x32_bf16 v[92:95], v[144:147], v[204:207], v[92:95]
	v_mfma_f32_16x16x32_bf16 v[88:91], v[152:155], v[204:207], v[88:91]
	v_mfma_f32_16x16x32_bf16 v[76:79], v[144:147], v[222:225], v[76:79]
	v_mfma_f32_16x16x32_bf16 v[72:75], v[152:155], v[222:225], v[72:75]
	v_mfma_f32_16x16x32_bf16 v[116:119], v[156:159], v[184:187], v[116:119]
	v_mfma_f32_16x16x32_bf16 v[112:115], v[170:173], v[184:187], v[112:115]
	v_mfma_f32_16x16x32_bf16 v[100:103], v[156:159], v[192:195], v[100:103]
	v_mfma_f32_16x16x32_bf16 v[96:99], v[170:173], v[192:195], v[96:99]
	v_mfma_f32_16x16x32_bf16 v[84:87], v[156:159], v[200:203], v[84:87]
	v_mfma_f32_16x16x32_bf16 v[80:83], v[170:173], v[200:203], v[80:83]
	v_mfma_f32_16x16x32_bf16 v[68:71], v[156:159], v[218:221], v[68:71]
	v_mfma_f32_16x16x32_bf16 v[64:67], v[170:173], v[218:221], v[64:67]
	v_mfma_f32_16x16x32_bf16 v[116:119], v[160:163], v[188:191], v[116:119]
	v_mfma_f32_16x16x32_bf16 v[112:115], v[180:183], v[188:191], v[112:115]
	v_mfma_f32_16x16x32_bf16 v[100:103], v[160:163], v[196:199], v[100:103]
	v_mfma_f32_16x16x32_bf16 v[96:99], v[180:183], v[196:199], v[96:99]
	v_mfma_f32_16x16x32_bf16 v[84:87], v[160:163], v[204:207], v[84:87]
	v_mfma_f32_16x16x32_bf16 v[80:83], v[180:183], v[204:207], v[80:83]
	v_mfma_f32_16x16x32_bf16 v[68:71], v[160:163], v[222:225], v[68:71]
	v_mfma_f32_16x16x32_bf16 v[64:67], v[180:183], v[222:225], v[64:67]
	s_barrier
; #define PG8_STAGE(bufoff, gbase, voff) do { _Pragma("unroll") for (int _i = 0; _i < 2; ++_i) \
;         __builtin_amdgcn_global_load_lds((const unsigned*)((const char*)(gbase) + (voff)[_i]), (PG8_LAS unsigned*)(lds + (bufoff) + ldsw + _i * 8192), 16, 0, 0); } while (0)
; #define PG8_LDA(dst, b, h) do { _Pragma("unroll") for (int m = 0; m < 4; ++m) _Pragma("unroll") for (int k = 0; k < 2; ++k) dst[m][k] = *(const PG8_LAS bf16x8*)(lds + PG8_SA(b, h) + aoff + m * 2048 + k * 1024); } while (0)
; #define PG8_MMA(ai, bj, At, Bt) do { __builtin_amdgcn_s_setprio(1); _Pragma("unroll") for (int m = 0; m < 4; ++m) _Pragma("unroll") for (int n = 0; n < 2; ++n) _Pragma("unroll") for (int k = 0; k < 2; ++k) \
;         acc[ai][bj][m][n] = __builtin_amdgcn_mfma_f32_16x16x32_bf16(Bt[n][k], At[m][k], acc[ai][bj][m][n], 0, 0, 0); __builtin_amdgcn_s_setprio(0); } while (0)
; #define PG8_WAIT_V(n) asm volatile("s_waitcnt vmcnt(" #n ")" ::: "memory")
; #define PG8_WAIT_L(n) asm volatile("s_waitcnt lgkmcnt(" #n ")" ::: "memory")
; #define PG8_BAR __builtin_amdgcn_s_barrier()
; #define PG8_SCHED __builtin_amdgcn_sched_barrier(0)
;     __device__ __forceinline__ void operator()(const f32x4 (&acc)[2][2][4][2], const Unit& u, int wr, int wc, int fr, int fq, int ui, PG8_LAS unsigned char* lds) const {
;     ...
;         const int sec = (u.pn * BM) >> 10;
;         int act = 0; float sc = 1.f;
;         if (mode == 0) act = (sec == 0 || sec == 3) ? 1 : (sec == 1 ? 2 : 0);
;         else if (mode == 1) sc = (sec == 0) ? qscale : 1.f;
;         else act = 3;
; template <class Epi, class Sched, bool ALIGN_EPI = false, bool SP2 = false>
; __device__ __forceinline__ void gemm_phase(PG8_LAS unsigned char* lds, const Gemm g, const Sched& S, const Epi& E) {
;     ...
;             PG8_LDA(At, 1, 1); PG8_STAGE(PG8_SB(1, 0), b3, voffB); PG8_STAGE(PG8_SB(1, 1), b3 + hstep, voffB); PG8_STAGE(PG8_SA(1, 0), a3, voffA);
;             PG8_WAIT_V(8); PG8_WAIT_L(0); PG8_BAR; PG8_MMA(1, 0, At, B0); PG8_MMA(1, 1, At, B1); PG8_BAR; PG8_SCHED;
	s_setprio 0
	s_add_i32 s48, s56, s8
	v_lshl_add_u64 v[176:177], v[176:177], 0, s[4:5]
	s_mov_b32 m0, s48
	ds_read_b128 v[184:187], v168 offset:49152
	ds_read_b128 v[188:191], v168 offset:50176
	ds_read_b128 v[192:195], v168 offset:51200
	ds_read_b128 v[196:199], v168 offset:52224
	ds_read_b128 v[200:203], v168 offset:53248
	ds_read_b128 v[204:207], v168 offset:54272
	ds_read_b128 v[218:221], v168 offset:55296
	ds_read_b128 v[222:225], v168 offset:56320
	global_load_lds_dwordx4 v[176:177], off
	s_add_i32 m0, s48, 0x2000
	s_add_u32 s46, s46, 0x40080
	v_lshl_add_u64 v[176:177], v[178:179], 0, s[4:5]
	s_addc_u32 s47, s47, 0
	s_add_i32 s48, s57, s8
	global_load_lds_dwordx4 v[176:177], off
	v_lshl_add_u64 v[176:177], s[46:47], 0, v[174:175]
	s_mov_b32 m0, s48
	s_nop 0
	global_load_lds_dwordx4 v[176:177], off
	v_lshl_add_u64 v[176:177], s[46:47], 0, v[136:137]
	s_add_i32 m0, s48, 0x2000
	s_nop 0
	global_load_lds_dwordx4 v[176:177], off
	v_lshl_add_u64 v[176:177], v[208:209], 0, s[4:5]
	s_mov_b32 m0, s93
	s_nop 0
	global_load_lds_dwordx4 v[176:177], off
	v_lshl_add_u64 v[176:177], v[226:227], 0, s[4:5]
	s_mov_b32 m0, s66
	s_nop 0
	global_load_lds_dwordx4 v[176:177], off
	s_waitcnt vmcnt(8)
	s_waitcnt lgkmcnt(0)
	s_setprio 1
	s_barrier
	v_mfma_f32_16x16x32_bf16 v[60:63], v[128:131], v[184:187], v[60:63]
	v_mfma_f32_16x16x32_bf16 v[56:59], v[148:151], v[184:187], v[56:59]
	v_mfma_f32_16x16x32_bf16 v[44:47], v[128:131], v[192:195], v[44:47]
	v_mfma_f32_16x16x32_bf16 v[40:43], v[148:151], v[192:195], v[40:43]
	v_mfma_f32_16x16x32_bf16 v[28:31], v[128:131], v[200:203], v[28:31]
	v_mfma_f32_16x16x32_bf16 v[24:27], v[148:151], v[200:203], v[24:27]
	v_mfma_f32_16x16x32_bf16 v[12:15], v[128:131], v[218:221], v[12:15]
	v_mfma_f32_16x16x32_bf16 v[8:11], v[148:151], v[218:221], v[8:11]
	v_mfma_f32_16x16x32_bf16 v[60:63], v[144:147], v[188:191], v[60:63]
	v_mfma_f32_16x16x32_bf16 v[56:59], v[152:155], v[188:191], v[56:59]
	v_mfma_f32_16x16x32_bf16 v[44:47], v[144:147], v[196:199], v[44:47]
	v_mfma_f32_16x16x32_bf16 v[40:43], v[152:155], v[196:199], v[40:43]
	v_mfma_f32_16x16x32_bf16 v[28:31], v[144:147], v[204:207], v[28:31]
	v_mfma_f32_16x16x32_bf16 v[24:27], v[152:155], v[204:207], v[24:27]
	v_mfma_f32_16x16x32_bf16 v[12:15], v[144:147], v[222:225], v[12:15]
	v_mfma_f32_16x16x32_bf16 v[8:11], v[152:155], v[222:225], v[8:11]
	v_mfma_f32_16x16x32_bf16 v[52:55], v[156:159], v[184:187], v[52:55]
	v_mfma_f32_16x16x32_bf16 v[48:51], v[170:173], v[184:187], v[48:51]
	v_mfma_f32_16x16x32_bf16 v[36:39], v[156:159], v[192:195], v[36:39]
	v_mfma_f32_16x16x32_bf16 v[32:35], v[170:173], v[192:195], v[32:35]
	v_mfma_f32_16x16x32_bf16 v[20:23], v[156:159], v[200:203], v[20:23]
	v_mfma_f32_16x16x32_bf16 v[16:19], v[170:173], v[200:203], v[16:19]
	v_mfma_f32_16x16x32_bf16 v[4:7], v[156:159], v[218:221], v[4:7]
	v_mfma_f32_16x16x32_bf16 v[0:3], v[170:173], v[218:221], v[0:3]
	v_mfma_f32_16x16x32_bf16 v[52:55], v[160:163], v[188:191], v[52:55]
	v_mfma_f32_16x16x32_bf16 v[48:51], v[180:183], v[188:191], v[48:51]
	v_mfma_f32_16x16x32_bf16 v[36:39], v[160:163], v[196:199], v[36:39]
	v_mfma_f32_16x16x32_bf16 v[32:35], v[180:183], v[196:199], v[32:35]
	v_mfma_f32_16x16x32_bf16 v[20:23], v[160:163], v[204:207], v[20:23]
	v_mfma_f32_16x16x32_bf16 v[16:19], v[180:183], v[204:207], v[16:19]
	v_mfma_f32_16x16x32_bf16 v[4:7], v[160:163], v[222:225], v[4:7]
	v_mfma_f32_16x16x32_bf16 v[0:3], v[180:183], v[222:225], v[0:3]
	s_barrier
	s_setprio 0
	s_add_i32 vcc_lo, vcc_lo, 2
	s_add_u32 s38, s38, 0x100
	s_addc_u32 s39, s39, 0
	s_add_u32 s71, s71, 0x100
	s_addc_u32 s73, s73, 0
	s_cmp_gt_u32 vcc_lo, 13
	s_cbranch_scc0 .LBB0_219
	s_cmp_eq_u64 s[82:83], 0
	s_cbranch_scc1 .Lep1_skip
	s_setprio 1
.Lep1_skip:
.LBB0_222:
	s_ashr_i32 s71, s0, 2
	s_cmp_lt_u32 s0, 4
	s_cselect_b64 s[46:47], -1, 0
	s_andn2_b64 vcc, exec, s[60:61]
	s_mov_b64 s[38:39], -1
	s_cbranch_vccnz .LBB0_224
	s_cmp_eq_u32 s71, 3
	s_cselect_b64 s[38:39], -1, 0
	s_or_b64 s[38:39], s[46:47], s[38:39]
	s_cmp_eq_u32 s71, 1
	s_cselect_b32 s48, 2, 0
	s_and_b64 s[38:39], s[38:39], exec
	s_cselect_b32 s48, 1, s48
	s_mov_b64 s[38:39], 0

; #define PG8_BAR __builtin_amdgcn_s_barrier()
; template <class Epi, class Sched, bool ALIGN_EPI = false, bool SP2 = false>
; __device__ __forceinline__ void gemm_phase(PG8_LAS unsigned char* lds, const Gemm g, const Sched& S, const Epi& E) {
;     ...
;     for (;;) {
;         const bool has_next = S.next(ui + 1, nxt);
;         const char* nA = has_next ? (const char*)g.A + (size_t)nxt.pm * tstep + (size_t)nxt.pn * g.a_gs : cA; const char* nB = has_next ? (const char*)g.Bt + (size_t)nxt.pn * tstep : cB;
;     ...
;         cur = nxt; cA = nA; cB = nB; ++ui;
;         if constexpr (ALIGN_EPI) { if (wr == 1) PG8_BAR; }
.LBB0_1629:
	s_setprio 0
	s_andn2_b64 vcc, exec, s[0:1]
	s_mov_b32 s16, s51
	s_mov_b32 s77, s76
	s_mov_b64 s[38:39], s[64:65]
	s_mov_b64 s[0:1], s[62:63]
	s_cbranch_vccz .LBB0_1671

; #define PG8_STAGE(bufoff, gbase, voff) do { _Pragma("unroll") for (int _i = 0; _i < 2; ++_i) \
;         __builtin_amdgcn_global_load_lds((const unsigned*)((const char*)(gbase) + (voff)[_i]), (PG8_LAS unsigned*)(lds + (bufoff) + ldsw + _i * 8192), 16, 0, 0); } while (0)
; #define PG8_LDA(dst, b, h) do { _Pragma("unroll") for (int m = 0; m < 4; ++m) _Pragma("unroll") for (int k = 0; k < 2; ++k) dst[m][k] = *(const PG8_LAS bf16x8*)(lds + PG8_SA(b, h) + aoff + m * 2048 + k * 1024); } while (0)
; #define PG8_LDB(dst, b, h) do { _Pragma("unroll") for (int n = 0; n < 2; ++n) _Pragma("unroll") for (int k = 0; k < 2; ++k) dst[n][k] = *(const PG8_LAS bf16x8*)(lds + PG8_SB(b, h) + boff + n * 2048 + k * 1024); } while (0)
; #define PG8_MMA(ai, bj, At, Bt) do { __builtin_amdgcn_s_setprio(1); _Pragma("unroll") for (int m = 0; m < 4; ++m) _Pragma("unroll") for (int n = 0; n < 2; ++n) _Pragma("unroll") for (int k = 0; k < 2; ++k) \
;         acc[ai][bj][m][n] = __builtin_amdgcn_mfma_f32_16x16x32_bf16(Bt[n][k], At[m][k], acc[ai][bj][m][n], 0, 0, 0); __builtin_amdgcn_s_setprio(0); } while (0)
; #define PG8_WAIT_V(n) asm volatile("s_waitcnt vmcnt(" #n ")" ::: "memory")
; #define PG8_WAIT_L(n) asm volatile("s_waitcnt lgkmcnt(" #n ")" ::: "memory")
; #define PG8_BAR __builtin_amdgcn_s_barrier()
; #define PG8_SCHED __builtin_amdgcn_sched_barrier(0)
; template <class Epi, class Sched, bool ALIGN_EPI = false, bool SP2 = false>
; __device__ __forceinline__ void gemm_phase(PG8_LAS unsigned char* lds, const Gemm g, const Sched& S, const Epi& E) {
;     ...
;             PG8_LDB(B0, 0, 0); PG8_LDB(B1, 0, 1); PG8_SCHED; PG8_LDA(At, 0, 0); PG8_STAGE(PG8_SA(1, 1), a1 + hstep, voffA);
;             PG8_WAIT_V(8); PG8_WAIT_L(0); PG8_BAR; PG8_MMA(0, 0, At, B0); PG8_MMA(0, 1, At, B1); PG8_BAR; PG8_SCHED;
;             PG8_LDA(At, 0, 1); PG8_STAGE(PG8_SB(0, 0), b2, voffB); PG8_STAGE(PG8_SB(0, 1), b2 + hstep, voffB); PG8_STAGE(PG8_SA(0, 0), a2, voffA);
.LBB0_1641:
	s_add_i32 s78, s38, 2
	s_add_u32 s79, s0, 0x80
	s_addc_u32 s39, s1, 0
	s_add_i32 s93, 0, 0x10000
	s_cmp_eq_u32 s75, s38
	s_cselect_b32 s39, s63, s39
	s_cselect_b32 s38, s62, s79
	s_cselect_b32 s95, s65, s45
	s_cselect_b32 s94, s64, s44
	s_add_i32 s79, 0, 0x14000
	v_add_u32_e32 v68, s93, v218
	v_add_u32_e32 v156, s79, v218
	ds_read_b128 v[56:59], v68
	ds_read_b128 v[60:63], v68 offset:1024
	ds_read_b128 v[64:67], v68 offset:2048
	ds_read_b128 v[68:71], v68 offset:3072
	ds_read_b128 v[144:147], v156
	ds_read_b128 v[148:151], v156 offset:1024
	ds_read_b128 v[152:155], v156 offset:2048
	ds_read_b128 v[156:159], v156 offset:3072
	v_lshl_add_u64 v[172:173], s[0:1], 0, v[186:187]
	s_add_i32 m0, s9, 0xc000
	ds_read_b128 v[160:163], v220
	ds_read_b128 v[164:167], v220 offset:1024
	ds_read_b128 v[168:171], v220 offset:2048
	ds_read_b128 v[176:179], v220 offset:3072
	ds_read_b128 v[190:193], v220 offset:4096
	ds_read_b128 v[194:197], v220 offset:5120
	ds_read_b128 v[198:201], v220 offset:6144
	ds_read_b128 v[202:205], v220 offset:7168
	global_load_lds_dwordx4 v[172:173], off
	v_lshl_add_u64 v[172:173], s[0:1], 0, v[188:189]
	s_add_i32 m0, s9, 0xe000
	s_nop 0
	global_load_lds_dwordx4 v[172:173], off
	s_waitcnt vmcnt(8)
	s_waitcnt lgkmcnt(0)
	s_setprio 1
	s_barrier
	v_mfma_f32_16x16x32_bf16 v[140:143], v[56:59], v[160:163], v[140:143]
	v_mfma_f32_16x16x32_bf16 v[136:139], v[64:67], v[160:163], v[136:139]
	v_mfma_f32_16x16x32_bf16 v[124:127], v[56:59], v[168:171], v[124:127]
	v_mfma_f32_16x16x32_bf16 v[120:123], v[64:67], v[168:171], v[120:123]
	v_mfma_f32_16x16x32_bf16 v[108:111], v[56:59], v[190:193], v[108:111]
	v_mfma_f32_16x16x32_bf16 v[104:107], v[64:67], v[190:193], v[104:107]
	v_mfma_f32_16x16x32_bf16 v[92:95], v[56:59], v[198:201], v[92:95]
	v_mfma_f32_16x16x32_bf16 v[88:91], v[64:67], v[198:201], v[88:91]
	v_mfma_f32_16x16x32_bf16 v[140:143], v[60:63], v[164:167], v[140:143]
	v_mfma_f32_16x16x32_bf16 v[136:139], v[68:71], v[164:167], v[136:139]
	v_mfma_f32_16x16x32_bf16 v[124:127], v[60:63], v[176:179], v[124:127]
	v_mfma_f32_16x16x32_bf16 v[120:123], v[68:71], v[176:179], v[120:123]
	v_mfma_f32_16x16x32_bf16 v[108:111], v[60:63], v[194:197], v[108:111]
	v_mfma_f32_16x16x32_bf16 v[104:107], v[68:71], v[194:197], v[104:107]
	v_mfma_f32_16x16x32_bf16 v[92:95], v[60:63], v[202:205], v[92:95]
	v_mfma_f32_16x16x32_bf16 v[88:91], v[68:71], v[202:205], v[88:91]
	v_mfma_f32_16x16x32_bf16 v[132:135], v[144:147], v[160:163], v[132:135]
	v_mfma_f32_16x16x32_bf16 v[128:131], v[152:155], v[160:163], v[128:131]
	v_mfma_f32_16x16x32_bf16 v[116:119], v[144:147], v[168:171], v[116:119]
	v_mfma_f32_16x16x32_bf16 v[112:115], v[152:155], v[168:171], v[112:115]
	v_mfma_f32_16x16x32_bf16 v[100:103], v[144:147], v[190:193], v[100:103]
	v_mfma_f32_16x16x32_bf16 v[96:99], v[152:155], v[190:193], v[96:99]
	v_mfma_f32_16x16x32_bf16 v[84:87], v[144:147], v[198:201], v[84:87]
	v_mfma_f32_16x16x32_bf16 v[80:83], v[152:155], v[198:201], v[80:83]
	v_mfma_f32_16x16x32_bf16 v[132:135], v[148:151], v[164:167], v[132:135]
	v_mfma_f32_16x16x32_bf16 v[128:131], v[156:159], v[164:167], v[128:131]
	v_mfma_f32_16x16x32_bf16 v[116:119], v[148:151], v[176:179], v[116:119]
	v_mfma_f32_16x16x32_bf16 v[112:115], v[156:159], v[176:179], v[112:115]
	v_mfma_f32_16x16x32_bf16 v[100:103], v[148:151], v[194:197], v[100:103]
	v_mfma_f32_16x16x32_bf16 v[96:99], v[156:159], v[194:197], v[96:99]
	v_mfma_f32_16x16x32_bf16 v[84:87], v[148:151], v[202:205], v[84:87]
	v_mfma_f32_16x16x32_bf16 v[80:83], v[156:159], v[202:205], v[80:83]
	s_barrier
	s_setprio 0
	s_add_i32 s93, s93, s8
	v_lshl_add_u64 v[172:173], s[94:95], 0, v[174:175]
	s_mov_b32 m0, s93
	ds_read_b128 v[160:163], v220 offset:16384
	ds_read_b128 v[164:167], v220 offset:17408
	ds_read_b128 v[168:171], v220 offset:18432
	ds_read_b128 v[176:179], v220 offset:19456
	ds_read_b128 v[190:193], v220 offset:20480
	ds_read_b128 v[194:197], v220 offset:21504
	ds_read_b128 v[198:201], v220 offset:22528
	ds_read_b128 v[202:205], v220 offset:23552
	global_load_lds_dwordx4 v[172:173], off
	s_add_i32 m0, s93, 0x2000
	v_lshl_add_u64 v[206:207], s[94:95], 0, v[180:181]
	s_add_u32 s94, s94, s50
	s_addc_u32 s95, s95, 0
	s_add_i32 s79, s79, s8
	global_load_lds_dwordx4 v[206:207], off
	v_lshl_add_u64 v[208:209], s[94:95], 0, v[174:175]
	s_mov_b32 m0, s79
	v_lshl_add_u64 v[222:223], s[94:95], 0, v[180:181]
	global_load_lds_dwordx4 v[208:209], off
	s_add_i32 m0, s79, 0x2000
	v_lshl_add_u64 v[224:225], s[38:39], 0, v[184:185]
	global_load_lds_dwordx4 v[222:223], off
	s_mov_b32 m0, s9
	v_lshl_add_u64 v[226:227], s[38:39], 0, v[182:183]
	global_load_lds_dwordx4 v[224:225], off
	s_mov_b32 m0, s67
	s_nop 0
	global_load_lds_dwordx4 v[226:227], off
	s_waitcnt vmcnt(8)
	s_waitcnt lgkmcnt(0)
	s_setprio 1
	s_barrier
; #define PG8_STAGE(bufoff, gbase, voff) do { _Pragma("unroll") for (int _i = 0; _i < 2; ++_i) \
;         __builtin_amdgcn_global_load_lds((const unsigned*)((const char*)(gbase) + (voff)[_i]), (PG8_LAS unsigned*)(lds + (bufoff) + ldsw + _i * 8192), 16, 0, 0); } while (0)
; #define PG8_LDA(dst, b, h) do { _Pragma("unroll") for (int m = 0; m < 4; ++m) _Pragma("unroll") for (int k = 0; k < 2; ++k) dst[m][k] = *(const PG8_LAS bf16x8*)(lds + PG8_SA(b, h) + aoff + m * 2048 + k * 1024); } while (0)
; #define PG8_LDB(dst, b, h) do { _Pragma("unroll") for (int n = 0; n < 2; ++n) _Pragma("unroll") for (int k = 0; k < 2; ++k) dst[n][k] = *(const PG8_LAS bf16x8*)(lds + PG8_SB(b, h) + boff + n * 2048 + k * 1024); } while (0)
; #define PG8_MMA(ai, bj, At, Bt) do { __builtin_amdgcn_s_setprio(1); _Pragma("unroll") for (int m = 0; m < 4; ++m) _Pragma("unroll") for (int n = 0; n < 2; ++n) _Pragma("unroll") for (int k = 0; k < 2; ++k) \
;         acc[ai][bj][m][n] = __builtin_amdgcn_mfma_f32_16x16x32_bf16(Bt[n][k], At[m][k], acc[ai][bj][m][n], 0, 0, 0); __builtin_amdgcn_s_setprio(0); } while (0)
; #define PG8_WAIT_V(n) asm volatile("s_waitcnt vmcnt(" #n ")" ::: "memory")
; #define PG8_WAIT_L(n) asm volatile("s_waitcnt lgkmcnt(" #n ")" ::: "memory")
; #define PG8_BAR __builtin_amdgcn_s_barrier()
; #define PG8_SCHED __builtin_amdgcn_sched_barrier(0)
; template <class Epi, class Sched, bool ALIGN_EPI = false, bool SP2 = false>
; __device__ __forceinline__ void gemm_phase(PG8_LAS unsigned char* lds, const Gemm g, const Sched& S, const Epi& E) {
;     ...
;             PG8_WAIT_V(8); PG8_WAIT_L(0); PG8_BAR; PG8_MMA(1, 0, At, B0); PG8_MMA(1, 1, At, B1); PG8_BAR; PG8_SCHED;
;             PG8_LDB(B0, 1, 0); PG8_LDB(B1, 1, 1); PG8_SCHED; PG8_LDA(At, 1, 0); PG8_STAGE(PG8_SA(0, 1), a2 + hstep, voffA);
;             PG8_WAIT_V(8); PG8_WAIT_L(0); PG8_BAR; PG8_MMA(0, 0, At, B0); PG8_MMA(0, 1, At, B1); PG8_BAR; PG8_SCHED;
	v_mfma_f32_16x16x32_bf16 v[76:79], v[56:59], v[160:163], v[76:79]
	v_mfma_f32_16x16x32_bf16 v[72:75], v[64:67], v[160:163], v[72:75]
	v_mfma_f32_16x16x32_bf16 v[44:47], v[56:59], v[168:171], v[44:47]
	v_mfma_f32_16x16x32_bf16 v[40:43], v[64:67], v[168:171], v[40:43]
	v_mfma_f32_16x16x32_bf16 v[28:31], v[56:59], v[190:193], v[28:31]
	v_mfma_f32_16x16x32_bf16 v[24:27], v[64:67], v[190:193], v[24:27]
	v_mfma_f32_16x16x32_bf16 v[12:15], v[56:59], v[198:201], v[12:15]
	v_mfma_f32_16x16x32_bf16 v[8:11], v[64:67], v[198:201], v[8:11]
	v_mfma_f32_16x16x32_bf16 v[76:79], v[60:63], v[164:167], v[76:79]
	v_mfma_f32_16x16x32_bf16 v[72:75], v[68:71], v[164:167], v[72:75]
	v_mfma_f32_16x16x32_bf16 v[44:47], v[60:63], v[176:179], v[44:47]
	v_mfma_f32_16x16x32_bf16 v[40:43], v[68:71], v[176:179], v[40:43]
	v_mfma_f32_16x16x32_bf16 v[28:31], v[60:63], v[194:197], v[28:31]
	v_mfma_f32_16x16x32_bf16 v[24:27], v[68:71], v[194:197], v[24:27]
	v_mfma_f32_16x16x32_bf16 v[12:15], v[60:63], v[202:205], v[12:15]
	v_mfma_f32_16x16x32_bf16 v[8:11], v[68:71], v[202:205], v[8:11]
	v_mfma_f32_16x16x32_bf16 v[52:55], v[144:147], v[160:163], v[52:55]
	v_mfma_f32_16x16x32_bf16 v[48:51], v[152:155], v[160:163], v[48:51]
	v_mfma_f32_16x16x32_bf16 v[36:39], v[144:147], v[168:171], v[36:39]
	v_mfma_f32_16x16x32_bf16 v[32:35], v[152:155], v[168:171], v[32:35]
	v_mfma_f32_16x16x32_bf16 v[20:23], v[144:147], v[190:193], v[20:23]
	v_mfma_f32_16x16x32_bf16 v[16:19], v[152:155], v[190:193], v[16:19]
	v_mfma_f32_16x16x32_bf16 v[4:7], v[144:147], v[198:201], v[4:7]
	v_mfma_f32_16x16x32_bf16 v[0:3], v[152:155], v[198:201], v[0:3]
	v_mfma_f32_16x16x32_bf16 v[52:55], v[148:151], v[164:167], v[52:55]
	v_mfma_f32_16x16x32_bf16 v[48:51], v[156:159], v[164:167], v[48:51]
	v_mfma_f32_16x16x32_bf16 v[36:39], v[148:151], v[176:179], v[36:39]
	v_mfma_f32_16x16x32_bf16 v[32:35], v[156:159], v[176:179], v[32:35]
	v_mfma_f32_16x16x32_bf16 v[20:23], v[148:151], v[194:197], v[20:23]
	v_mfma_f32_16x16x32_bf16 v[16:19], v[156:159], v[194:197], v[16:19]
	v_mfma_f32_16x16x32_bf16 v[4:7], v[148:151], v[202:205], v[4:7]
	v_mfma_f32_16x16x32_bf16 v[0:3], v[156:159], v[202:205], v[0:3]
	s_barrier
	s_setprio 0
	s_add_i32 s79, 0, 0x18000
	s_add_i32 s93, 0, 0x1c000
	v_add_u32_e32 v68, s79, v218
	v_add_u32_e32 v156, s93, v218
	ds_read_b128 v[56:59], v68
	ds_read_b128 v[60:63], v68 offset:1024
	ds_read_b128 v[64:67], v68 offset:2048
	ds_read_b128 v[68:71], v68 offset:3072
	ds_read_b128 v[144:147], v156
	ds_read_b128 v[148:151], v156 offset:1024
	ds_read_b128 v[152:155], v156 offset:2048
	ds_read_b128 v[156:159], v156 offset:3072
	s_add_u32 s38, s38, s50
	s_addc_u32 s39, s39, 0
	s_mov_b32 m0, s68
	v_lshl_add_u64 v[228:229], s[38:39], 0, v[184:185]
	ds_read_b128 v[160:163], v220 offset:32768
	ds_read_b128 v[164:167], v220 offset:33792
	ds_read_b128 v[168:171], v220 offset:34816
	ds_read_b128 v[176:179], v220 offset:35840
	ds_read_b128 v[190:193], v220 offset:36864
	ds_read_b128 v[194:197], v220 offset:37888
	ds_read_b128 v[198:201], v220 offset:38912
	ds_read_b128 v[202:205], v220 offset:39936
	global_load_lds_dwordx4 v[228:229], off
	v_lshl_add_u64 v[228:229], s[38:39], 0, v[182:183]
	s_mov_b32 m0, s69
	s_nop 0
	global_load_lds_dwordx4 v[228:229], off
	s_waitcnt vmcnt(8)
	s_waitcnt lgkmcnt(0)
	s_setprio 1
	s_barrier
	v_mfma_f32_16x16x32_bf16 v[140:143], v[56:59], v[160:163], v[140:143]
	v_mfma_f32_16x16x32_bf16 v[136:139], v[64:67], v[160:163], v[136:139]
	v_mfma_f32_16x16x32_bf16 v[124:127], v[56:59], v[168:171], v[124:127]
	v_mfma_f32_16x16x32_bf16 v[120:123], v[64:67], v[168:171], v[120:123]
	v_mfma_f32_16x16x32_bf16 v[108:111], v[56:59], v[190:193], v[108:111]
	v_mfma_f32_16x16x32_bf16 v[104:107], v[64:67], v[190:193], v[104:107]
	v_mfma_f32_16x16x32_bf16 v[92:95], v[56:59], v[198:201], v[92:95]
	v_mfma_f32_16x16x32_bf16 v[88:91], v[64:67], v[198:201], v[88:91]
	v_mfma_f32_16x16x32_bf16 v[140:143], v[60:63], v[164:167], v[140:143]
	v_mfma_f32_16x16x32_bf16 v[136:139], v[68:71], v[164:167], v[136:139]
	v_mfma_f32_16x16x32_bf16 v[124:127], v[60:63], v[176:179], v[124:127]
	v_mfma_f32_16x16x32_bf16 v[120:123], v[68:71], v[176:179], v[120:123]
	v_mfma_f32_16x16x32_bf16 v[108:111], v[60:63], v[194:197], v[108:111]
	v_mfma_f32_16x16x32_bf16 v[104:107], v[68:71], v[194:197], v[104:107]
	v_mfma_f32_16x16x32_bf16 v[92:95], v[60:63], v[202:205], v[92:95]
	v_mfma_f32_16x16x32_bf16 v[88:91], v[68:71], v[202:205], v[88:91]
	v_mfma_f32_16x16x32_bf16 v[132:135], v[144:147], v[160:163], v[132:135]
	v_mfma_f32_16x16x32_bf16 v[128:131], v[152:155], v[160:163], v[128:131]
	v_mfma_f32_16x16x32_bf16 v[116:119], v[144:147], v[168:171], v[116:119]
	v_mfma_f32_16x16x32_bf16 v[112:115], v[152:155], v[168:171], v[112:115]
	v_mfma_f32_16x16x32_bf16 v[100:103], v[144:147], v[190:193], v[100:103]
	v_mfma_f32_16x16x32_bf16 v[96:99], v[152:155], v[190:193], v[96:99]
	v_mfma_f32_16x16x32_bf16 v[84:87], v[144:147], v[198:201], v[84:87]
	v_mfma_f32_16x16x32_bf16 v[80:83], v[152:155], v[198:201], v[80:83]
	v_mfma_f32_16x16x32_bf16 v[132:135], v[148:151], v[164:167], v[132:135]
	v_mfma_f32_16x16x32_bf16 v[128:131], v[156:159], v[164:167], v[128:131]
	v_mfma_f32_16x16x32_bf16 v[116:119], v[148:151], v[176:179], v[116:119]
	v_mfma_f32_16x16x32_bf16 v[112:115], v[156:159], v[176:179], v[112:115]
	v_mfma_f32_16x16x32_bf16 v[100:103], v[148:151], v[194:197], v[100:103]
	v_mfma_f32_16x16x32_bf16 v[96:99], v[156:159], v[194:197], v[96:99]
	v_mfma_f32_16x16x32_bf16 v[84:87], v[148:151], v[202:205], v[84:87]
	v_mfma_f32_16x16x32_bf16 v[80:83], v[156:159], v[202:205], v[80:83]
	s_barrier
; #define PG8_STAGE(bufoff, gbase, voff) do { _Pragma("unroll") for (int _i = 0; _i < 2; ++_i) \
;         __builtin_amdgcn_global_load_lds((const unsigned*)((const char*)(gbase) + (voff)[_i]), (PG8_LAS unsigned*)(lds + (bufoff) + ldsw + _i * 8192), 16, 0, 0); } while (0)
; #define PG8_LDA(dst, b, h) do { _Pragma("unroll") for (int m = 0; m < 4; ++m) _Pragma("unroll") for (int k = 0; k < 2; ++k) dst[m][k] = *(const PG8_LAS bf16x8*)(lds + PG8_SA(b, h) + aoff + m * 2048 + k * 1024); } while (0)
; #define PG8_MMA(ai, bj, At, Bt) do { __builtin_amdgcn_s_setprio(1); _Pragma("unroll") for (int m = 0; m < 4; ++m) _Pragma("unroll") for (int n = 0; n < 2; ++n) _Pragma("unroll") for (int k = 0; k < 2; ++k) \
;         acc[ai][bj][m][n] = __builtin_amdgcn_mfma_f32_16x16x32_bf16(Bt[n][k], At[m][k], acc[ai][bj][m][n], 0, 0, 0); __builtin_amdgcn_s_setprio(0); } while (0)
; #define PG8_WAIT_V(n) asm volatile("s_waitcnt vmcnt(" #n ")" ::: "memory")
; #define PG8_WAIT_L(n) asm volatile("s_waitcnt lgkmcnt(" #n ")" ::: "memory")
; #define PG8_BAR __builtin_amdgcn_s_barrier()
; #define PG8_SCHED __builtin_amdgcn_sched_barrier(0)
;     __device__ __forceinline__ void operator()(const f32x4 (&acc)[2][2][4][2], const Unit& u, int wr, int wc, int fr, int fq, int, PG8_LAS unsigned char*) const {
;         const int row0 = u.pm * BM + wr * 64 + fr, col0 = u.pn * BM + wc * 32 + 8 * fq;
;         f32x4 csv[2][2];
; #pragma unroll
;         for (int bj = 0; bj < 2; ++bj)
; #pragma unroll
;             for (int n = 0; n < 2; ++n) { csv[bj][n] = (f32x4){1.f, 1.f, 1.f, 1.f}; if (cscale) csv[bj][n] = *(const f32x4*)(cscale + col0 + bj * HALF + 4 * n); }
; template <class Epi, class Sched, bool ALIGN_EPI = false, bool SP2 = false>
; __device__ __forceinline__ void gemm_phase(PG8_LAS unsigned char* lds, const Gemm g, const Sched& S, const Epi& E) {
;     ...
;             PG8_LDA(At, 1, 1); PG8_STAGE(PG8_SB(1, 0), b3, voffB); PG8_STAGE(PG8_SB(1, 1), b3 + hstep, voffB); PG8_STAGE(PG8_SA(1, 0), a3, voffA);
;             PG8_WAIT_V(8); PG8_WAIT_L(0); PG8_BAR; PG8_MMA(1, 0, At, B0); PG8_MMA(1, 1, At, B1); PG8_BAR; PG8_SCHED;
	s_setprio 0
	s_add_i32 s38, s79, s8
	v_lshl_add_u64 v[172:173], v[172:173], 0, s[4:5]
	s_mov_b32 m0, s38
	ds_read_b128 v[160:163], v220 offset:49152
	ds_read_b128 v[164:167], v220 offset:50176
	ds_read_b128 v[168:171], v220 offset:51200
	ds_read_b128 v[176:179], v220 offset:52224
	ds_read_b128 v[190:193], v220 offset:53248
	ds_read_b128 v[194:197], v220 offset:54272
	ds_read_b128 v[198:201], v220 offset:55296
	ds_read_b128 v[202:205], v220 offset:56320
	global_load_lds_dwordx4 v[172:173], off
	v_lshl_add_u64 v[172:173], v[206:207], 0, s[4:5]
	s_add_i32 m0, s38, 0x2000
	s_add_i32 s38, s93, s8
	global_load_lds_dwordx4 v[172:173], off
	v_lshl_add_u64 v[172:173], v[208:209], 0, s[4:5]
	s_mov_b32 m0, s38
	s_nop 0
	global_load_lds_dwordx4 v[172:173], off
	v_lshl_add_u64 v[172:173], v[222:223], 0, s[4:5]
	s_add_i32 m0, s38, 0x2000
	s_nop 0
	global_load_lds_dwordx4 v[172:173], off
	v_lshl_add_u64 v[172:173], v[224:225], 0, s[4:5]
	s_mov_b32 m0, s73
	s_nop 0
	global_load_lds_dwordx4 v[172:173], off
	v_lshl_add_u64 v[172:173], v[226:227], 0, s[4:5]
	s_mov_b32 m0, s74
	s_nop 0
	global_load_lds_dwordx4 v[172:173], off
	s_waitcnt vmcnt(8)
	s_waitcnt lgkmcnt(0)
	s_setprio 1
	s_barrier
	v_mfma_f32_16x16x32_bf16 v[76:79], v[56:59], v[160:163], v[76:79]
	v_mfma_f32_16x16x32_bf16 v[72:75], v[64:67], v[160:163], v[72:75]
	v_mfma_f32_16x16x32_bf16 v[44:47], v[56:59], v[168:171], v[44:47]
	v_mfma_f32_16x16x32_bf16 v[40:43], v[64:67], v[168:171], v[40:43]
	v_mfma_f32_16x16x32_bf16 v[28:31], v[56:59], v[190:193], v[28:31]
	v_mfma_f32_16x16x32_bf16 v[24:27], v[64:67], v[190:193], v[24:27]
	v_mfma_f32_16x16x32_bf16 v[12:15], v[56:59], v[198:201], v[12:15]
	v_mfma_f32_16x16x32_bf16 v[8:11], v[64:67], v[198:201], v[8:11]
	v_mfma_f32_16x16x32_bf16 v[76:79], v[60:63], v[164:167], v[76:79]
	v_mfma_f32_16x16x32_bf16 v[72:75], v[68:71], v[164:167], v[72:75]
	v_mfma_f32_16x16x32_bf16 v[44:47], v[60:63], v[176:179], v[44:47]
	v_mfma_f32_16x16x32_bf16 v[40:43], v[68:71], v[176:179], v[40:43]
	v_mfma_f32_16x16x32_bf16 v[28:31], v[60:63], v[194:197], v[28:31]
	v_mfma_f32_16x16x32_bf16 v[24:27], v[68:71], v[194:197], v[24:27]
	v_mfma_f32_16x16x32_bf16 v[12:15], v[60:63], v[202:205], v[12:15]
	v_mfma_f32_16x16x32_bf16 v[8:11], v[68:71], v[202:205], v[8:11]
	v_mfma_f32_16x16x32_bf16 v[52:55], v[144:147], v[160:163], v[52:55]
	v_mfma_f32_16x16x32_bf16 v[48:51], v[152:155], v[160:163], v[48:51]
	v_mfma_f32_16x16x32_bf16 v[36:39], v[144:147], v[168:171], v[36:39]
	v_mfma_f32_16x16x32_bf16 v[32:35], v[152:155], v[168:171], v[32:35]
	v_mfma_f32_16x16x32_bf16 v[20:23], v[144:147], v[190:193], v[20:23]
	v_mfma_f32_16x16x32_bf16 v[16:19], v[152:155], v[190:193], v[16:19]
	v_mfma_f32_16x16x32_bf16 v[4:7], v[144:147], v[198:201], v[4:7]
	v_mfma_f32_16x16x32_bf16 v[0:3], v[152:155], v[198:201], v[0:3]
	v_mfma_f32_16x16x32_bf16 v[52:55], v[148:151], v[164:167], v[52:55]
	v_mfma_f32_16x16x32_bf16 v[48:51], v[156:159], v[164:167], v[48:51]
	v_mfma_f32_16x16x32_bf16 v[36:39], v[148:151], v[176:179], v[36:39]
	v_mfma_f32_16x16x32_bf16 v[32:35], v[156:159], v[176:179], v[32:35]
	v_mfma_f32_16x16x32_bf16 v[20:23], v[148:151], v[194:197], v[20:23]
	v_mfma_f32_16x16x32_bf16 v[16:19], v[156:159], v[194:197], v[16:19]
	v_mfma_f32_16x16x32_bf16 v[4:7], v[148:151], v[202:205], v[4:7]
	v_mfma_f32_16x16x32_bf16 v[0:3], v[156:159], v[202:205], v[0:3]
	s_barrier
	s_setprio 0
	s_add_u32 s0, s0, 0x100
	s_addc_u32 s1, s1, 0
	s_add_u32 s44, s44, 0x100
	s_addc_u32 s45, s45, 0
	s_cmp_ge_u32 s78, s72
	s_mov_b32 s38, s78
	s_cbranch_scc0 .LBB0_1641
	s_cmp_eq_u64 s[54:55], 0
	s_cbranch_scc1 .Lep2_skip
	s_setprio 1
.Lep2_skip:
.LBB0_1644:
	v_lshl_or_b32 v190, s16, 8, v219
	v_ashrrev_i32_e32 v191, 31, v190
	v_cndmask_b32_e64 v56, 0, 1, s[60:61]
	v_lshl_add_u64 v[144:145], v[190:191], 2, s[56:57]
	v_mov_b32_e32 v64, 1.0
	v_cmp_ne_u32_e64 s[44:45], 1, v56
	s_andn2_b64 vcc, exec, s[60:61]
	v_mov_b32_e32 v68, 1.0
	v_mov_b32_e32 v69, 1.0
	v_mov_b32_e32 v70, 1.0
	v_mov_b32_e32 v71, 1.0
	s_cbranch_vccnz .LBB0_1646
	global_load_dwordx4 v[68:71], v[144:145], off

; #define PG8_BAR __builtin_amdgcn_s_barrier()
; template <class Epi, class Sched, bool ALIGN_EPI = false, bool SP2 = false>
; __device__ __forceinline__ void gemm_phase(PG8_LAS unsigned char* lds, const Gemm g, const Sched& S, const Epi& E) {
;     ...
;     for (;;) {
;         const bool has_next = S.next(ui + 1, nxt);
;         const char* nA = has_next ? (const char*)g.A + (size_t)nxt.pm * tstep + (size_t)nxt.pn * g.a_gs : cA; const char* nB = has_next ? (const char*)g.Bt + (size_t)nxt.pn * tstep : cB;
;     ...
;         cur = nxt; cA = nA; cB = nB; ++ui;
;         if constexpr (ALIGN_EPI) { if (wr == 1) PG8_BAR; }
.LBB0_1744:
	s_setprio 0
	s_andn2_b64 vcc, exec, s[0:1]
	s_mov_b32 s65, s48
	s_mov_b32 s67, s50
	s_mov_b64 s[38:39], s[54:55]
	s_mov_b64 s[0:1], s[52:53]
	s_mov_b32 s68, s64
	s_cbranch_vccz .LBB0_1774

; #define PG8_STAGE(bufoff, gbase, voff) do { _Pragma("unroll") for (int _i = 0; _i < 2; ++_i) \
;         __builtin_amdgcn_global_load_lds((const unsigned*)((const char*)(gbase) + (voff)[_i]), (PG8_LAS unsigned*)(lds + (bufoff) + ldsw + _i * 8192), 16, 0, 0); } while (0)
; #define PG8_LDA(dst, b, h) do { _Pragma("unroll") for (int m = 0; m < 4; ++m) _Pragma("unroll") for (int k = 0; k < 2; ++k) dst[m][k] = *(const PG8_LAS bf16x8*)(lds + PG8_SA(b, h) + aoff + m * 2048 + k * 1024); } while (0)
; #define PG8_LDB(dst, b, h) do { _Pragma("unroll") for (int n = 0; n < 2; ++n) _Pragma("unroll") for (int k = 0; k < 2; ++k) dst[n][k] = *(const PG8_LAS bf16x8*)(lds + PG8_SB(b, h) + boff + n * 2048 + k * 1024); } while (0)
; #define PG8_MMA(ai, bj, At, Bt) do { __builtin_amdgcn_s_setprio(1); _Pragma("unroll") for (int m = 0; m < 4; ++m) _Pragma("unroll") for (int n = 0; n < 2; ++n) _Pragma("unroll") for (int k = 0; k < 2; ++k) \
;         acc[ai][bj][m][n] = __builtin_amdgcn_mfma_f32_16x16x32_bf16(Bt[n][k], At[m][k], acc[ai][bj][m][n], 0, 0, 0); __builtin_amdgcn_s_setprio(0); } while (0)
; #define PG8_WAIT_V(n) asm volatile("s_waitcnt vmcnt(" #n ")" ::: "memory")
; #define PG8_WAIT_L(n) asm volatile("s_waitcnt lgkmcnt(" #n ")" ::: "memory")
; #define PG8_BAR __builtin_amdgcn_s_barrier()
; #define PG8_SCHED __builtin_amdgcn_sched_barrier(0)
; template <class Epi, class Sched, bool ALIGN_EPI = false, bool SP2 = false>
; __device__ __forceinline__ void gemm_phase(PG8_LAS unsigned char* lds, const Gemm g, const Sched& S, const Epi& E) {
;     ...
;             PG8_LDB(B0, 0, 0); PG8_LDB(B1, 0, 1); PG8_SCHED; PG8_LDA(At, 0, 0); PG8_STAGE(PG8_SA(1, 1), a1 + hstep, voffA);
;             PG8_WAIT_V(8); PG8_WAIT_L(0); PG8_BAR; PG8_MMA(0, 0, At, B0); PG8_MMA(0, 1, At, B1); PG8_BAR; PG8_SCHED;
;             PG8_LDA(At, 0, 1); PG8_STAGE(PG8_SB(0, 0), b2, voffB); PG8_STAGE(PG8_SB(0, 1), b2 + hstep, voffB); PG8_STAGE(PG8_SA(0, 0), a2, voffA);
.LBB0_1752:
	s_add_u32 s38, s0, 0xfffc0080
	s_addc_u32 s39, s1, -1
	s_add_i32 s74, 0, 0x10000
	s_cmp_eq_u32 s73, 12
	s_cselect_b32 s57, s51, s39
	s_cselect_b32 s56, s69, s38
	v_add_u32_e32 v151, s74, v147
	s_cselect_b32 s39, s49, s72
	s_cselect_b32 s38, s70, s71
	s_add_i32 s76, 0, 0x14000
	ds_read_b128 v[138:141], v151
	ds_read_b128 v[142:145], v151 offset:1024
	ds_read_b128 v[152:155], v151 offset:2048
	ds_read_b128 v[156:159], v151 offset:3072
	v_add_u32_e32 v151, s76, v147
	ds_read_b128 v[160:163], v151
	ds_read_b128 v[164:167], v151 offset:1024
	ds_read_b128 v[168:171], v151 offset:2048
	ds_read_b128 v[176:179], v151 offset:3072
	v_lshl_add_u64 v[172:173], s[0:1], 0, v[134:135]
	s_add_i32 m0, s58, 0xc000
	ds_read_b128 v[180:183], v150
	ds_read_b128 v[184:187], v150 offset:1024
	ds_read_b128 v[188:191], v150 offset:2048
	ds_read_b128 v[192:195], v150 offset:3072
	ds_read_b128 v[196:199], v150 offset:4096
	ds_read_b128 v[200:203], v150 offset:5120
	ds_read_b128 v[204:207], v150 offset:6144
	ds_read_b128 v[218:221], v150 offset:7168
	global_load_lds_dwordx4 v[172:173], off
	v_lshl_add_u64 v[172:173], s[0:1], 0, v[136:137]
	s_add_i32 m0, s58, 0xe000
	s_nop 0
	global_load_lds_dwordx4 v[172:173], off
	s_waitcnt vmcnt(8)
	s_waitcnt lgkmcnt(0)
	s_setprio 1
	s_barrier
	v_mfma_f32_16x16x32_bf16 v[124:127], v[138:141], v[180:183], v[124:127]
	v_mfma_f32_16x16x32_bf16 v[120:123], v[152:155], v[180:183], v[120:123]
	v_mfma_f32_16x16x32_bf16 v[108:111], v[138:141], v[188:191], v[108:111]
	v_mfma_f32_16x16x32_bf16 v[104:107], v[152:155], v[188:191], v[104:107]
	v_mfma_f32_16x16x32_bf16 v[92:95], v[138:141], v[196:199], v[92:95]
	v_mfma_f32_16x16x32_bf16 v[88:91], v[152:155], v[196:199], v[88:91]
	v_mfma_f32_16x16x32_bf16 v[76:79], v[138:141], v[204:207], v[76:79]
	v_mfma_f32_16x16x32_bf16 v[72:75], v[152:155], v[204:207], v[72:75]
	v_mfma_f32_16x16x32_bf16 v[124:127], v[142:145], v[184:187], v[124:127]
	v_mfma_f32_16x16x32_bf16 v[120:123], v[156:159], v[184:187], v[120:123]
	v_mfma_f32_16x16x32_bf16 v[108:111], v[142:145], v[192:195], v[108:111]
	v_mfma_f32_16x16x32_bf16 v[104:107], v[156:159], v[192:195], v[104:107]
	v_mfma_f32_16x16x32_bf16 v[92:95], v[142:145], v[200:203], v[92:95]
	v_mfma_f32_16x16x32_bf16 v[88:91], v[156:159], v[200:203], v[88:91]
	v_mfma_f32_16x16x32_bf16 v[76:79], v[142:145], v[218:221], v[76:79]
	v_mfma_f32_16x16x32_bf16 v[72:75], v[156:159], v[218:221], v[72:75]
	v_mfma_f32_16x16x32_bf16 v[116:119], v[160:163], v[180:183], v[116:119]
	v_mfma_f32_16x16x32_bf16 v[112:115], v[168:171], v[180:183], v[112:115]
	v_mfma_f32_16x16x32_bf16 v[100:103], v[160:163], v[188:191], v[100:103]
	v_mfma_f32_16x16x32_bf16 v[96:99], v[168:171], v[188:191], v[96:99]
	v_mfma_f32_16x16x32_bf16 v[84:87], v[160:163], v[196:199], v[84:87]
	v_mfma_f32_16x16x32_bf16 v[80:83], v[168:171], v[196:199], v[80:83]
	v_mfma_f32_16x16x32_bf16 v[68:71], v[160:163], v[204:207], v[68:71]
	v_mfma_f32_16x16x32_bf16 v[64:67], v[168:171], v[204:207], v[64:67]
	v_mfma_f32_16x16x32_bf16 v[116:119], v[164:167], v[184:187], v[116:119]
	v_mfma_f32_16x16x32_bf16 v[112:115], v[176:179], v[184:187], v[112:115]
	v_mfma_f32_16x16x32_bf16 v[100:103], v[164:167], v[192:195], v[100:103]
	v_mfma_f32_16x16x32_bf16 v[96:99], v[176:179], v[192:195], v[96:99]
	v_mfma_f32_16x16x32_bf16 v[84:87], v[164:167], v[200:203], v[84:87]
	v_mfma_f32_16x16x32_bf16 v[80:83], v[176:179], v[200:203], v[80:83]
	v_mfma_f32_16x16x32_bf16 v[68:71], v[164:167], v[218:221], v[68:71]
	v_mfma_f32_16x16x32_bf16 v[64:67], v[176:179], v[218:221], v[64:67]
	s_barrier
	s_setprio 0
	s_add_i32 s74, s74, s8
	v_lshl_add_u64 v[172:173], s[38:39], 0, v[174:175]
	s_mov_b32 m0, s74
	ds_read_b128 v[180:183], v150 offset:16384
	ds_read_b128 v[184:187], v150 offset:17408
	ds_read_b128 v[188:191], v150 offset:18432
	ds_read_b128 v[192:195], v150 offset:19456
	ds_read_b128 v[196:199], v150 offset:20480
	ds_read_b128 v[200:203], v150 offset:21504
	ds_read_b128 v[204:207], v150 offset:22528
	ds_read_b128 v[218:221], v150 offset:23552
	global_load_lds_dwordx4 v[172:173], off
	s_add_i32 m0, s74, 0x2000
	s_add_u32 s74, s38, 0x40000
	v_lshl_add_u64 v[208:209], s[38:39], 0, v[128:129]
	s_addc_u32 s75, s39, 0
	s_add_i32 s76, s76, s8
	global_load_lds_dwordx4 v[208:209], off
	v_lshl_add_u64 v[222:223], s[74:75], 0, v[174:175]
	s_mov_b32 m0, s76
	v_lshl_add_u64 v[224:225], s[56:57], 0, v[130:131]
	global_load_lds_dwordx4 v[222:223], off
	v_lshl_add_u64 v[222:223], s[74:75], 0, v[128:129]
	s_add_i32 m0, s76, 0x2000
	s_nop 0
	global_load_lds_dwordx4 v[222:223], off
	v_lshl_add_u64 v[222:223], s[56:57], 0, v[132:133]
	s_mov_b32 m0, s58
	s_nop 0
	global_load_lds_dwordx4 v[222:223], off
	s_mov_b32 m0, s59
	s_nop 0
	global_load_lds_dwordx4 v[224:225], off
	s_waitcnt vmcnt(8)
	s_waitcnt lgkmcnt(0)
	s_setprio 1
	s_barrier
; #define PG8_STAGE(bufoff, gbase, voff) do { _Pragma("unroll") for (int _i = 0; _i < 2; ++_i) \
;         __builtin_amdgcn_global_load_lds((const unsigned*)((const char*)(gbase) + (voff)[_i]), (PG8_LAS unsigned*)(lds + (bufoff) + ldsw + _i * 8192), 16, 0, 0); } while (0)
; #define PG8_LDA(dst, b, h) do { _Pragma("unroll") for (int m = 0; m < 4; ++m) _Pragma("unroll") for (int k = 0; k < 2; ++k) dst[m][k] = *(const PG8_LAS bf16x8*)(lds + PG8_SA(b, h) + aoff + m * 2048 + k * 1024); } while (0)
; #define PG8_LDB(dst, b, h) do { _Pragma("unroll") for (int n = 0; n < 2; ++n) _Pragma("unroll") for (int k = 0; k < 2; ++k) dst[n][k] = *(const PG8_LAS bf16x8*)(lds + PG8_SB(b, h) + boff + n * 2048 + k * 1024); } while (0)
; #define PG8_MMA(ai, bj, At, Bt) do { __builtin_amdgcn_s_setprio(1); _Pragma("unroll") for (int m = 0; m < 4; ++m) _Pragma("unroll") for (int n = 0; n < 2; ++n) _Pragma("unroll") for (int k = 0; k < 2; ++k) \
;         acc[ai][bj][m][n] = __builtin_amdgcn_mfma_f32_16x16x32_bf16(Bt[n][k], At[m][k], acc[ai][bj][m][n], 0, 0, 0); __builtin_amdgcn_s_setprio(0); } while (0)
; #define PG8_WAIT_V(n) asm volatile("s_waitcnt vmcnt(" #n ")" ::: "memory")
; #define PG8_WAIT_L(n) asm volatile("s_waitcnt lgkmcnt(" #n ")" ::: "memory")
; #define PG8_BAR __builtin_amdgcn_s_barrier()
; #define PG8_SCHED __builtin_amdgcn_sched_barrier(0)
; template <class Epi, class Sched, bool ALIGN_EPI = false, bool SP2 = false>
; __device__ __forceinline__ void gemm_phase(PG8_LAS unsigned char* lds, const Gemm g, const Sched& S, const Epi& E) {
;     ...
;             PG8_WAIT_V(8); PG8_WAIT_L(0); PG8_BAR; PG8_MMA(1, 0, At, B0); PG8_MMA(1, 1, At, B1); PG8_BAR; PG8_SCHED;
;             PG8_LDB(B0, 1, 0); PG8_LDB(B1, 1, 1); PG8_SCHED; PG8_LDA(At, 1, 0); PG8_STAGE(PG8_SA(0, 1), a2 + hstep, voffA);
;             PG8_WAIT_V(8); PG8_WAIT_L(0); PG8_BAR; PG8_MMA(0, 0, At, B0); PG8_MMA(0, 1, At, B1); PG8_BAR; PG8_SCHED;
	v_mfma_f32_16x16x32_bf16 v[60:63], v[138:141], v[180:183], v[60:63]
	v_mfma_f32_16x16x32_bf16 v[56:59], v[152:155], v[180:183], v[56:59]
	v_mfma_f32_16x16x32_bf16 v[44:47], v[138:141], v[188:191], v[44:47]
	v_mfma_f32_16x16x32_bf16 v[40:43], v[152:155], v[188:191], v[40:43]
	v_mfma_f32_16x16x32_bf16 v[28:31], v[138:141], v[196:199], v[28:31]
	v_mfma_f32_16x16x32_bf16 v[24:27], v[152:155], v[196:199], v[24:27]
	v_mfma_f32_16x16x32_bf16 v[12:15], v[138:141], v[204:207], v[12:15]
	v_mfma_f32_16x16x32_bf16 v[8:11], v[152:155], v[204:207], v[8:11]
	v_mfma_f32_16x16x32_bf16 v[60:63], v[142:145], v[184:187], v[60:63]
	v_mfma_f32_16x16x32_bf16 v[56:59], v[156:159], v[184:187], v[56:59]
	v_mfma_f32_16x16x32_bf16 v[44:47], v[142:145], v[192:195], v[44:47]
	v_mfma_f32_16x16x32_bf16 v[40:43], v[156:159], v[192:195], v[40:43]
	v_mfma_f32_16x16x32_bf16 v[28:31], v[142:145], v[200:203], v[28:31]
	v_mfma_f32_16x16x32_bf16 v[24:27], v[156:159], v[200:203], v[24:27]
	v_mfma_f32_16x16x32_bf16 v[12:15], v[142:145], v[218:221], v[12:15]
	v_mfma_f32_16x16x32_bf16 v[8:11], v[156:159], v[218:221], v[8:11]
	v_mfma_f32_16x16x32_bf16 v[52:55], v[160:163], v[180:183], v[52:55]
	v_mfma_f32_16x16x32_bf16 v[48:51], v[168:171], v[180:183], v[48:51]
	v_mfma_f32_16x16x32_bf16 v[36:39], v[160:163], v[188:191], v[36:39]
	v_mfma_f32_16x16x32_bf16 v[32:35], v[168:171], v[188:191], v[32:35]
	v_mfma_f32_16x16x32_bf16 v[20:23], v[160:163], v[196:199], v[20:23]
	v_mfma_f32_16x16x32_bf16 v[16:19], v[168:171], v[196:199], v[16:19]
	v_mfma_f32_16x16x32_bf16 v[4:7], v[160:163], v[204:207], v[4:7]
	v_mfma_f32_16x16x32_bf16 v[0:3], v[168:171], v[204:207], v[0:3]
	v_mfma_f32_16x16x32_bf16 v[52:55], v[164:167], v[184:187], v[52:55]
	v_mfma_f32_16x16x32_bf16 v[48:51], v[176:179], v[184:187], v[48:51]
	v_mfma_f32_16x16x32_bf16 v[36:39], v[164:167], v[192:195], v[36:39]
	v_mfma_f32_16x16x32_bf16 v[32:35], v[176:179], v[192:195], v[32:35]
	v_mfma_f32_16x16x32_bf16 v[20:23], v[164:167], v[200:203], v[20:23]
	v_mfma_f32_16x16x32_bf16 v[16:19], v[176:179], v[200:203], v[16:19]
	v_mfma_f32_16x16x32_bf16 v[4:7], v[164:167], v[218:221], v[4:7]
	v_mfma_f32_16x16x32_bf16 v[0:3], v[176:179], v[218:221], v[0:3]
	s_barrier
	s_setprio 0
	s_add_i32 s74, 0, 0x18000
	v_add_u32_e32 v151, s74, v147
	s_add_i32 s75, 0, 0x1c000
	ds_read_b128 v[138:141], v151
	ds_read_b128 v[142:145], v151 offset:1024
	ds_read_b128 v[152:155], v151 offset:2048
	ds_read_b128 v[156:159], v151 offset:3072
	v_add_u32_e32 v151, s75, v147
	ds_read_b128 v[160:163], v151
	ds_read_b128 v[164:167], v151 offset:1024
	ds_read_b128 v[168:171], v151 offset:2048
	ds_read_b128 v[176:179], v151 offset:3072
	s_add_u32 s56, s56, 0x40000
	s_addc_u32 s57, s57, 0
	s_mov_b32 m0, s60
	v_lshl_add_u64 v[226:227], s[56:57], 0, v[132:133]
	ds_read_b128 v[180:183], v150 offset:32768
	ds_read_b128 v[184:187], v150 offset:33792
	ds_read_b128 v[188:191], v150 offset:34816
	ds_read_b128 v[192:195], v150 offset:35840
	ds_read_b128 v[196:199], v150 offset:36864
	ds_read_b128 v[200:203], v150 offset:37888
	ds_read_b128 v[204:207], v150 offset:38912
	ds_read_b128 v[218:221], v150 offset:39936
	global_load_lds_dwordx4 v[226:227], off
	v_lshl_add_u64 v[226:227], s[56:57], 0, v[130:131]
	s_mov_b32 m0, s61
	s_nop 0
	global_load_lds_dwordx4 v[226:227], off
	s_waitcnt vmcnt(8)
	s_waitcnt lgkmcnt(0)
	s_setprio 1
	s_barrier
	v_mfma_f32_16x16x32_bf16 v[124:127], v[138:141], v[180:183], v[124:127]
	v_mfma_f32_16x16x32_bf16 v[120:123], v[152:155], v[180:183], v[120:123]
	v_mfma_f32_16x16x32_bf16 v[108:111], v[138:141], v[188:191], v[108:111]
	v_mfma_f32_16x16x32_bf16 v[104:107], v[152:155], v[188:191], v[104:107]
	v_mfma_f32_16x16x32_bf16 v[92:95], v[138:141], v[196:199], v[92:95]
	v_mfma_f32_16x16x32_bf16 v[88:91], v[152:155], v[196:199], v[88:91]
	v_mfma_f32_16x16x32_bf16 v[76:79], v[138:141], v[204:207], v[76:79]
	v_mfma_f32_16x16x32_bf16 v[72:75], v[152:155], v[204:207], v[72:75]
	v_mfma_f32_16x16x32_bf16 v[124:127], v[142:145], v[184:187], v[124:127]
	v_mfma_f32_16x16x32_bf16 v[120:123], v[156:159], v[184:187], v[120:123]
	v_mfma_f32_16x16x32_bf16 v[108:111], v[142:145], v[192:195], v[108:111]
	v_mfma_f32_16x16x32_bf16 v[104:107], v[156:159], v[192:195], v[104:107]
	v_mfma_f32_16x16x32_bf16 v[92:95], v[142:145], v[200:203], v[92:95]
	v_mfma_f32_16x16x32_bf16 v[88:91], v[156:159], v[200:203], v[88:91]
	v_mfma_f32_16x16x32_bf16 v[76:79], v[142:145], v[218:221], v[76:79]
	v_mfma_f32_16x16x32_bf16 v[72:75], v[156:159], v[218:221], v[72:75]
	v_mfma_f32_16x16x32_bf16 v[116:119], v[160:163], v[180:183], v[116:119]
	v_mfma_f32_16x16x32_bf16 v[112:115], v[168:171], v[180:183], v[112:115]
	v_mfma_f32_16x16x32_bf16 v[100:103], v[160:163], v[188:191], v[100:103]
	v_mfma_f32_16x16x32_bf16 v[96:99], v[168:171], v[188:191], v[96:99]
	v_mfma_f32_16x16x32_bf16 v[84:87], v[160:163], v[196:199], v[84:87]
	v_mfma_f32_16x16x32_bf16 v[80:83], v[168:171], v[196:199], v[80:83]
	v_mfma_f32_16x16x32_bf16 v[68:71], v[160:163], v[204:207], v[68:71]
	v_mfma_f32_16x16x32_bf16 v[64:67], v[168:171], v[204:207], v[64:67]
	v_mfma_f32_16x16x32_bf16 v[116:119], v[164:167], v[184:187], v[116:119]
	v_mfma_f32_16x16x32_bf16 v[112:115], v[176:179], v[184:187], v[112:115]
	v_mfma_f32_16x16x32_bf16 v[100:103], v[164:167], v[192:195], v[100:103]
	v_mfma_f32_16x16x32_bf16 v[96:99], v[176:179], v[192:195], v[96:99]
	v_mfma_f32_16x16x32_bf16 v[84:87], v[164:167], v[200:203], v[84:87]
	v_mfma_f32_16x16x32_bf16 v[80:83], v[176:179], v[200:203], v[80:83]
	v_mfma_f32_16x16x32_bf16 v[68:71], v[164:167], v[218:221], v[68:71]
	v_mfma_f32_16x16x32_bf16 v[64:67], v[176:179], v[218:221], v[64:67]
	s_barrier
; #define PG8_LAS __attribute__((address_space(3)))
; #define PG8_STAGE(bufoff, gbase, voff) do { _Pragma("unroll") for (int _i = 0; _i < 2; ++_i) \
;         __builtin_amdgcn_global_load_lds((const unsigned*)((const char*)(gbase) + (voff)[_i]), (PG8_LAS unsigned*)(lds + (bufoff) + ldsw + _i * 8192), 16, 0, 0); } while (0)
; #define PG8_LDA(dst, b, h) do { _Pragma("unroll") for (int m = 0; m < 4; ++m) _Pragma("unroll") for (int k = 0; k < 2; ++k) dst[m][k] = *(const PG8_LAS bf16x8*)(lds + PG8_SA(b, h) + aoff + m * 2048 + k * 1024); } while (0)
; #define PG8_WAIT_V(n) asm volatile("s_waitcnt vmcnt(" #n ")" ::: "memory")
; #define PG8_WAIT_L(n) asm volatile("s_waitcnt lgkmcnt(" #n ")" ::: "memory")
; #define PG8_BAR __builtin_amdgcn_s_barrier()
;     __device__ __forceinline__ void operator()(const f32x4 (&acc)[2][2][4][2], const Unit& u, int wr, int wc, int fr, int fq, int ui, PG8_LAS unsigned char* lds) const {
;         const int row0 = u.pm * BM + wr * 64 + fr, col0 = u.pn * BM + wc * 32 + 8 * fq;
;         const PG8_LAS float* tab = (const PG8_LAS float*)(lds + RSTD_TAB) + ui * 256 + wr * 64 + fr;
;         const int sec = (u.pn * BM) >> 10;
;         int act = 0; float sc = 1.f;
;         if (mode == 0) act = (sec == 0 || sec == 3) ? 1 : (sec == 1 ? 2 : 0);
;         else if (mode == 1) sc = (sec == 0) ? qscale : 1.f;
;         else act = 3;
;         const bool ksum = (mode == 1) && (sec == 1);
;         f32x4 csum[2][2] = {{(f32x4){0.f, 0.f, 0.f, 0.f}, (f32x4){0.f, 0.f, 0.f, 0.f}}, {(f32x4){0.f, 0.f, 0.f, 0.f}, (f32x4){0.f, 0.f, 0.f, 0.f}}};
; #pragma unroll
;         for (int ai = 0; ai < 2; ++ai) {
;             float rs4[4];
; #pragma unroll
;             for (int m = 0; m < 4; ++m) {
;                 if ((m & 1) == 0) {
;                     if (use_tab) { rs4[m] = tab[ai * HALF + m * 16] * sc; rs4[m + 1] = tab[ai * HALF + (m + 1) * 16] * sc; }
; template <class Epi, class Sched, bool ALIGN_EPI = false, bool SP2 = false>
; __device__ __forceinline__ void gemm_phase(PG8_LAS unsigned char* lds, const Gemm g, const Sched& S, const Epi& E) {
;     ...
;             PG8_LDA(At, 1, 1); PG8_STAGE(PG8_SB(1, 0), b3, voffB); PG8_STAGE(PG8_SB(1, 1), b3 + hstep, voffB); PG8_STAGE(PG8_SA(1, 0), a3, voffA);
;             PG8_WAIT_V(8); PG8_WAIT_L(0); PG8_BAR; PG8_MMA(1, 0, At, B0); PG8_MMA(1, 1, At, B1); PG8_BAR; PG8_SCHED;
	s_setprio 0
	s_add_i32 s56, s74, s8
	v_lshl_add_u64 v[172:173], v[172:173], 0, s[4:5]
	s_mov_b32 m0, s56
	ds_read_b128 v[180:183], v150 offset:49152
	ds_read_b128 v[184:187], v150 offset:50176
	ds_read_b128 v[188:191], v150 offset:51200
	ds_read_b128 v[192:195], v150 offset:52224
	ds_read_b128 v[196:199], v150 offset:53248
	ds_read_b128 v[200:203], v150 offset:54272
	ds_read_b128 v[204:207], v150 offset:55296
	ds_read_b128 v[218:221], v150 offset:56320
	global_load_lds_dwordx4 v[172:173], off
	s_add_i32 m0, s56, 0x2000
	s_add_u32 s38, s38, 0x40080
	v_lshl_add_u64 v[172:173], v[208:209], 0, s[4:5]
	s_addc_u32 s39, s39, 0
	s_add_i32 s56, s75, s8
	global_load_lds_dwordx4 v[172:173], off
	v_lshl_add_u64 v[172:173], s[38:39], 0, v[174:175]
	s_mov_b32 m0, s56
	s_nop 0
	global_load_lds_dwordx4 v[172:173], off
	v_lshl_add_u64 v[172:173], s[38:39], 0, v[128:129]
	s_add_i32 m0, s56, 0x2000
	s_nop 0
	global_load_lds_dwordx4 v[172:173], off
	v_lshl_add_u64 v[172:173], v[222:223], 0, s[4:5]
	s_mov_b32 m0, s62
	s_nop 0
	global_load_lds_dwordx4 v[172:173], off
	v_lshl_add_u64 v[172:173], v[224:225], 0, s[4:5]
	s_mov_b32 m0, s63
	s_nop 0
	global_load_lds_dwordx4 v[172:173], off
	s_waitcnt vmcnt(8)
	s_waitcnt lgkmcnt(0)
	s_setprio 1
	s_barrier
	v_mfma_f32_16x16x32_bf16 v[60:63], v[138:141], v[180:183], v[60:63]
	v_mfma_f32_16x16x32_bf16 v[56:59], v[152:155], v[180:183], v[56:59]
	v_mfma_f32_16x16x32_bf16 v[44:47], v[138:141], v[188:191], v[44:47]
	v_mfma_f32_16x16x32_bf16 v[40:43], v[152:155], v[188:191], v[40:43]
	v_mfma_f32_16x16x32_bf16 v[28:31], v[138:141], v[196:199], v[28:31]
	v_mfma_f32_16x16x32_bf16 v[24:27], v[152:155], v[196:199], v[24:27]
	v_mfma_f32_16x16x32_bf16 v[12:15], v[138:141], v[204:207], v[12:15]
	v_mfma_f32_16x16x32_bf16 v[8:11], v[152:155], v[204:207], v[8:11]
	v_mfma_f32_16x16x32_bf16 v[60:63], v[142:145], v[184:187], v[60:63]
	v_mfma_f32_16x16x32_bf16 v[56:59], v[156:159], v[184:187], v[56:59]
	v_mfma_f32_16x16x32_bf16 v[44:47], v[142:145], v[192:195], v[44:47]
	v_mfma_f32_16x16x32_bf16 v[40:43], v[156:159], v[192:195], v[40:43]
	v_mfma_f32_16x16x32_bf16 v[28:31], v[142:145], v[200:203], v[28:31]
	v_mfma_f32_16x16x32_bf16 v[24:27], v[156:159], v[200:203], v[24:27]
	v_mfma_f32_16x16x32_bf16 v[12:15], v[142:145], v[218:221], v[12:15]
	v_mfma_f32_16x16x32_bf16 v[8:11], v[156:159], v[218:221], v[8:11]
	v_mfma_f32_16x16x32_bf16 v[52:55], v[160:163], v[180:183], v[52:55]
	v_mfma_f32_16x16x32_bf16 v[48:51], v[168:171], v[180:183], v[48:51]
	v_mfma_f32_16x16x32_bf16 v[36:39], v[160:163], v[188:191], v[36:39]
	v_mfma_f32_16x16x32_bf16 v[32:35], v[168:171], v[188:191], v[32:35]
	v_mfma_f32_16x16x32_bf16 v[20:23], v[160:163], v[196:199], v[20:23]
	v_mfma_f32_16x16x32_bf16 v[16:19], v[168:171], v[196:199], v[16:19]
	v_mfma_f32_16x16x32_bf16 v[4:7], v[160:163], v[204:207], v[4:7]
	v_mfma_f32_16x16x32_bf16 v[0:3], v[168:171], v[204:207], v[0:3]
	v_mfma_f32_16x16x32_bf16 v[52:55], v[164:167], v[184:187], v[52:55]
	v_mfma_f32_16x16x32_bf16 v[48:51], v[176:179], v[184:187], v[48:51]
	v_mfma_f32_16x16x32_bf16 v[36:39], v[164:167], v[192:195], v[36:39]
	v_mfma_f32_16x16x32_bf16 v[32:35], v[176:179], v[192:195], v[32:35]
	v_mfma_f32_16x16x32_bf16 v[20:23], v[164:167], v[200:203], v[20:23]
	v_mfma_f32_16x16x32_bf16 v[16:19], v[176:179], v[200:203], v[16:19]
	v_mfma_f32_16x16x32_bf16 v[4:7], v[164:167], v[218:221], v[4:7]
	v_mfma_f32_16x16x32_bf16 v[0:3], v[176:179], v[218:221], v[0:3]
	s_barrier
	s_setprio 0
	s_add_i32 s73, s73, 2
	s_add_u32 s0, s0, 0x100
	s_addc_u32 s1, s1, 0
	s_add_u32 s71, s71, 0x100
	s_addc_u32 s72, s72, 0
	s_cmp_gt_u32 s73, 13
	s_cbranch_scc0 .LBB0_1752
	s_cmp_eq_u64 s[44:45], 0
	s_cbranch_scc1 .Lep3_skip
	s_setprio 1
.Lep3_skip:
.LBB0_1755:
	v_lshl_add_u32 v140, s67, 8, v146
	s_lshl_b32 s38, s68, 10
	v_or_b32_e32 v144, 16, v140
	s_mov_b64 s[0:1], -1
	s_and_b64 vcc, exec, s[40:41]
	v_add_u32_e32 v151, s38, v148
	v_ashrrev_i32_e32 v141, 31, v140
	v_ashrrev_i32_e32 v145, 31, v144
	s_cbranch_vccnz .LBB0_1757
	ds_read2_b32 v[142:143], v151 offset1:16
	s_mov_b64 s[0:1], 0

; #define PG8_BAR __builtin_amdgcn_s_barrier()
; template <class Epi, class Sched, bool ALIGN_EPI = false, bool SP2 = false>
; __device__ __forceinline__ void gemm_phase(PG8_LAS unsigned char* lds, const Gemm g, const Sched& S, const Epi& E) {
;     ...
;     for (;;) {
;         const bool has_next = S.next(ui + 1, nxt);
;         const char* nA = has_next ? (const char*)g.A + (size_t)nxt.pm * tstep + (size_t)nxt.pn * g.a_gs : cA; const char* nB = has_next ? (const char*)g.Bt + (size_t)nxt.pn * tstep : cB;
;     ...
;         cur = nxt; cA = nA; cB = nB; ++ui;
;         if constexpr (ALIGN_EPI) { if (wr == 1) PG8_BAR; }
.LBB0_1837:
	s_setprio 0
	s_andn2_b64 vcc, exec, s[0:1]
	s_mov_b32 s16, s46
	s_mov_b32 s68, s48
	s_mov_b64 s[54:55], s[52:53]
	s_mov_b64 s[0:1], s[50:51]
	s_cbranch_vccz .LBB0_1867

; #define PG8_STAGE(bufoff, gbase, voff) do { _Pragma("unroll") for (int _i = 0; _i < 2; ++_i) \
;         __builtin_amdgcn_global_load_lds((const unsigned*)((const char*)(gbase) + (voff)[_i]), (PG8_LAS unsigned*)(lds + (bufoff) + ldsw + _i * 8192), 16, 0, 0); } while (0)
; #define PG8_LDA(dst, b, h) do { _Pragma("unroll") for (int m = 0; m < 4; ++m) _Pragma("unroll") for (int k = 0; k < 2; ++k) dst[m][k] = *(const PG8_LAS bf16x8*)(lds + PG8_SA(b, h) + aoff + m * 2048 + k * 1024); } while (0)
; #define PG8_LDB(dst, b, h) do { _Pragma("unroll") for (int n = 0; n < 2; ++n) _Pragma("unroll") for (int k = 0; k < 2; ++k) dst[n][k] = *(const PG8_LAS bf16x8*)(lds + PG8_SB(b, h) + boff + n * 2048 + k * 1024); } while (0)
; #define PG8_MMA(ai, bj, At, Bt) do { __builtin_amdgcn_s_setprio(1); _Pragma("unroll") for (int m = 0; m < 4; ++m) _Pragma("unroll") for (int n = 0; n < 2; ++n) _Pragma("unroll") for (int k = 0; k < 2; ++k) \
;         acc[ai][bj][m][n] = __builtin_amdgcn_mfma_f32_16x16x32_bf16(Bt[n][k], At[m][k], acc[ai][bj][m][n], 0, 0, 0); __builtin_amdgcn_s_setprio(0); } while (0)
; #define PG8_WAIT_V(n) asm volatile("s_waitcnt vmcnt(" #n ")" ::: "memory")
; #define PG8_WAIT_L(n) asm volatile("s_waitcnt lgkmcnt(" #n ")" ::: "memory")
; #define PG8_BAR __builtin_amdgcn_s_barrier()
; #define PG8_SCHED __builtin_amdgcn_sched_barrier(0)
; template <class Epi, class Sched, bool ALIGN_EPI = false, bool SP2 = false>
; __device__ __forceinline__ void gemm_phase(PG8_LAS unsigned char* lds, const Gemm g, const Sched& S, const Epi& E) {
;     ...
;             PG8_LDB(B0, 0, 0); PG8_LDB(B1, 0, 1); PG8_SCHED; PG8_LDA(At, 0, 0); PG8_STAGE(PG8_SA(1, 1), a1 + hstep, voffA);
;             PG8_WAIT_V(8); PG8_WAIT_L(0); PG8_BAR; PG8_MMA(0, 0, At, B0); PG8_MMA(0, 1, At, B1); PG8_BAR; PG8_SCHED;
;             PG8_LDA(At, 0, 1); PG8_STAGE(PG8_SB(0, 0), b2, voffB); PG8_STAGE(PG8_SB(0, 1), b2 + hstep, voffB); PG8_STAGE(PG8_SA(0, 0), a2, voffA);
.LBB0_1845:
	s_add_u32 s54, s0, 0xfff00080
	s_addc_u32 s55, s1, -1
	s_add_i32 s74, 0, 0x10000
	s_cmp_eq_u32 s73, 60
	s_cselect_b32 s57, s49, s55
	s_cselect_b32 s56, s69, s54
	s_cselect_b32 s55, s47, s72
	s_cselect_b32 s54, s70, s71
	s_add_i32 s76, 0, 0x14000
	v_add_u32_e32 v140, s74, v189
	v_add_u32_e32 v166, s76, v189
	ds_read_b128 v[128:131], v140
	ds_read_b128 v[132:135], v140 offset:1024
	ds_read_b128 v[136:139], v140 offset:2048
	ds_read_b128 v[140:143], v140 offset:3072
	ds_read_b128 v[144:147], v166
	ds_read_b128 v[148:151], v166 offset:1024
	ds_read_b128 v[162:165], v166 offset:2048
	ds_read_b128 v[166:169], v166 offset:3072
	v_lshl_add_u64 v[208:209], s[0:1], 0, v[158:159]
	s_add_i32 m0, s59, 0xc000
	ds_read_b128 v[170:173], v191
	ds_read_b128 v[176:179], v191 offset:1024
	ds_read_b128 v[180:183], v191 offset:2048
	ds_read_b128 v[184:187], v191 offset:3072
	ds_read_b128 v[192:195], v191 offset:4096
	ds_read_b128 v[196:199], v191 offset:5120
	ds_read_b128 v[200:203], v191 offset:6144
	ds_read_b128 v[204:207], v191 offset:7168
	global_load_lds_dwordx4 v[208:209], off
	v_lshl_add_u64 v[208:209], s[0:1], 0, v[160:161]
	s_add_i32 m0, s59, 0xe000
	s_nop 0
	global_load_lds_dwordx4 v[208:209], off
	s_waitcnt vmcnt(8)
	s_waitcnt lgkmcnt(0)
	s_setprio 1
	s_barrier
	v_mfma_f32_16x16x32_bf16 v[124:127], v[128:131], v[170:173], v[124:127]
	v_mfma_f32_16x16x32_bf16 v[120:123], v[136:139], v[170:173], v[120:123]
	v_mfma_f32_16x16x32_bf16 v[108:111], v[128:131], v[180:183], v[108:111]
	v_mfma_f32_16x16x32_bf16 v[104:107], v[136:139], v[180:183], v[104:107]
	v_mfma_f32_16x16x32_bf16 v[92:95], v[128:131], v[192:195], v[92:95]
	v_mfma_f32_16x16x32_bf16 v[88:91], v[136:139], v[192:195], v[88:91]
	v_mfma_f32_16x16x32_bf16 v[76:79], v[128:131], v[200:203], v[76:79]
	v_mfma_f32_16x16x32_bf16 v[72:75], v[136:139], v[200:203], v[72:75]
	v_mfma_f32_16x16x32_bf16 v[124:127], v[132:135], v[176:179], v[124:127]
	v_mfma_f32_16x16x32_bf16 v[120:123], v[140:143], v[176:179], v[120:123]
	v_mfma_f32_16x16x32_bf16 v[108:111], v[132:135], v[184:187], v[108:111]
	v_mfma_f32_16x16x32_bf16 v[104:107], v[140:143], v[184:187], v[104:107]
	v_mfma_f32_16x16x32_bf16 v[92:95], v[132:135], v[196:199], v[92:95]
	v_mfma_f32_16x16x32_bf16 v[88:91], v[140:143], v[196:199], v[88:91]
	v_mfma_f32_16x16x32_bf16 v[76:79], v[132:135], v[204:207], v[76:79]
	v_mfma_f32_16x16x32_bf16 v[72:75], v[140:143], v[204:207], v[72:75]
	v_mfma_f32_16x16x32_bf16 v[116:119], v[144:147], v[170:173], v[116:119]
	v_mfma_f32_16x16x32_bf16 v[112:115], v[162:165], v[170:173], v[112:115]
	v_mfma_f32_16x16x32_bf16 v[100:103], v[144:147], v[180:183], v[100:103]
	v_mfma_f32_16x16x32_bf16 v[96:99], v[162:165], v[180:183], v[96:99]
	v_mfma_f32_16x16x32_bf16 v[84:87], v[144:147], v[192:195], v[84:87]
	v_mfma_f32_16x16x32_bf16 v[80:83], v[162:165], v[192:195], v[80:83]
	v_mfma_f32_16x16x32_bf16 v[68:71], v[144:147], v[200:203], v[68:71]
	v_mfma_f32_16x16x32_bf16 v[64:67], v[162:165], v[200:203], v[64:67]
	v_mfma_f32_16x16x32_bf16 v[116:119], v[148:151], v[176:179], v[116:119]
	v_mfma_f32_16x16x32_bf16 v[112:115], v[166:169], v[176:179], v[112:115]
	v_mfma_f32_16x16x32_bf16 v[100:103], v[148:151], v[184:187], v[100:103]
	v_mfma_f32_16x16x32_bf16 v[96:99], v[166:169], v[184:187], v[96:99]
	v_mfma_f32_16x16x32_bf16 v[84:87], v[148:151], v[196:199], v[84:87]
	v_mfma_f32_16x16x32_bf16 v[80:83], v[166:169], v[196:199], v[80:83]
	v_mfma_f32_16x16x32_bf16 v[68:71], v[148:151], v[204:207], v[68:71]
	v_mfma_f32_16x16x32_bf16 v[64:67], v[166:169], v[204:207], v[64:67]
	s_barrier
	s_setprio 0
	s_add_i32 s74, s74, s58
	v_lshl_add_u64 v[208:209], s[54:55], 0, v[174:175]
	s_mov_b32 m0, s74
	ds_read_b128 v[170:173], v191 offset:16384
	ds_read_b128 v[176:179], v191 offset:17408
	ds_read_b128 v[180:183], v191 offset:18432
	ds_read_b128 v[184:187], v191 offset:19456
	ds_read_b128 v[192:195], v191 offset:20480
	ds_read_b128 v[196:199], v191 offset:21504
	ds_read_b128 v[200:203], v191 offset:22528
	ds_read_b128 v[204:207], v191 offset:23552
	global_load_lds_dwordx4 v[208:209], off
	s_add_i32 m0, s74, 0x2000
	s_add_u32 s74, s54, 0x100000
	v_lshl_add_u64 v[218:219], s[54:55], 0, v[152:153]
	s_addc_u32 s75, s55, 0
	s_add_i32 s76, s76, s58
	global_load_lds_dwordx4 v[218:219], off
	v_lshl_add_u64 v[220:221], s[74:75], 0, v[174:175]
	s_mov_b32 m0, s76
	v_lshl_add_u64 v[222:223], s[56:57], 0, v[154:155]
	global_load_lds_dwordx4 v[220:221], off
	v_lshl_add_u64 v[220:221], s[74:75], 0, v[152:153]
	s_add_i32 m0, s76, 0x2000
	s_nop 0
	global_load_lds_dwordx4 v[220:221], off
	v_lshl_add_u64 v[220:221], s[56:57], 0, v[156:157]
	s_mov_b32 m0, s59
	s_nop 0
	global_load_lds_dwordx4 v[220:221], off
	s_mov_b32 m0, s60
	s_nop 0
	global_load_lds_dwordx4 v[222:223], off
	s_waitcnt vmcnt(8)
	s_waitcnt lgkmcnt(0)
	s_setprio 1
	s_barrier
; #define PG8_STAGE(bufoff, gbase, voff) do { _Pragma("unroll") for (int _i = 0; _i < 2; ++_i) \
;         __builtin_amdgcn_global_load_lds((const unsigned*)((const char*)(gbase) + (voff)[_i]), (PG8_LAS unsigned*)(lds + (bufoff) + ldsw + _i * 8192), 16, 0, 0); } while (0)
; #define PG8_LDA(dst, b, h) do { _Pragma("unroll") for (int m = 0; m < 4; ++m) _Pragma("unroll") for (int k = 0; k < 2; ++k) dst[m][k] = *(const PG8_LAS bf16x8*)(lds + PG8_SA(b, h) + aoff + m * 2048 + k * 1024); } while (0)
; #define PG8_LDB(dst, b, h) do { _Pragma("unroll") for (int n = 0; n < 2; ++n) _Pragma("unroll") for (int k = 0; k < 2; ++k) dst[n][k] = *(const PG8_LAS bf16x8*)(lds + PG8_SB(b, h) + boff + n * 2048 + k * 1024); } while (0)
; #define PG8_MMA(ai, bj, At, Bt) do { __builtin_amdgcn_s_setprio(1); _Pragma("unroll") for (int m = 0; m < 4; ++m) _Pragma("unroll") for (int n = 0; n < 2; ++n) _Pragma("unroll") for (int k = 0; k < 2; ++k) \
;         acc[ai][bj][m][n] = __builtin_amdgcn_mfma_f32_16x16x32_bf16(Bt[n][k], At[m][k], acc[ai][bj][m][n], 0, 0, 0); __builtin_amdgcn_s_setprio(0); } while (0)
; #define PG8_WAIT_V(n) asm volatile("s_waitcnt vmcnt(" #n ")" ::: "memory")
; #define PG8_WAIT_L(n) asm volatile("s_waitcnt lgkmcnt(" #n ")" ::: "memory")
; #define PG8_BAR __builtin_amdgcn_s_barrier()
; #define PG8_SCHED __builtin_amdgcn_sched_barrier(0)
; template <class Epi, class Sched, bool ALIGN_EPI = false, bool SP2 = false>
; __device__ __forceinline__ void gemm_phase(PG8_LAS unsigned char* lds, const Gemm g, const Sched& S, const Epi& E) {
;     ...
;             PG8_WAIT_V(8); PG8_WAIT_L(0); PG8_BAR; PG8_MMA(1, 0, At, B0); PG8_MMA(1, 1, At, B1); PG8_BAR; PG8_SCHED;
;             PG8_LDB(B0, 1, 0); PG8_LDB(B1, 1, 1); PG8_SCHED; PG8_LDA(At, 1, 0); PG8_STAGE(PG8_SA(0, 1), a2 + hstep, voffA);
;             PG8_WAIT_V(8); PG8_WAIT_L(0); PG8_BAR; PG8_MMA(0, 0, At, B0); PG8_MMA(0, 1, At, B1); PG8_BAR; PG8_SCHED;
	v_mfma_f32_16x16x32_bf16 v[60:63], v[128:131], v[170:173], v[60:63]
	v_mfma_f32_16x16x32_bf16 v[56:59], v[136:139], v[170:173], v[56:59]
	v_mfma_f32_16x16x32_bf16 v[44:47], v[128:131], v[180:183], v[44:47]
	v_mfma_f32_16x16x32_bf16 v[40:43], v[136:139], v[180:183], v[40:43]
	v_mfma_f32_16x16x32_bf16 v[28:31], v[128:131], v[192:195], v[28:31]
	v_mfma_f32_16x16x32_bf16 v[24:27], v[136:139], v[192:195], v[24:27]
	v_mfma_f32_16x16x32_bf16 v[12:15], v[128:131], v[200:203], v[12:15]
	v_mfma_f32_16x16x32_bf16 v[8:11], v[136:139], v[200:203], v[8:11]
	v_mfma_f32_16x16x32_bf16 v[60:63], v[132:135], v[176:179], v[60:63]
	v_mfma_f32_16x16x32_bf16 v[56:59], v[140:143], v[176:179], v[56:59]
	v_mfma_f32_16x16x32_bf16 v[44:47], v[132:135], v[184:187], v[44:47]
	v_mfma_f32_16x16x32_bf16 v[40:43], v[140:143], v[184:187], v[40:43]
	v_mfma_f32_16x16x32_bf16 v[28:31], v[132:135], v[196:199], v[28:31]
	v_mfma_f32_16x16x32_bf16 v[24:27], v[140:143], v[196:199], v[24:27]
	v_mfma_f32_16x16x32_bf16 v[12:15], v[132:135], v[204:207], v[12:15]
	v_mfma_f32_16x16x32_bf16 v[8:11], v[140:143], v[204:207], v[8:11]
	v_mfma_f32_16x16x32_bf16 v[52:55], v[144:147], v[170:173], v[52:55]
	v_mfma_f32_16x16x32_bf16 v[48:51], v[162:165], v[170:173], v[48:51]
	v_mfma_f32_16x16x32_bf16 v[36:39], v[144:147], v[180:183], v[36:39]
	v_mfma_f32_16x16x32_bf16 v[32:35], v[162:165], v[180:183], v[32:35]
	v_mfma_f32_16x16x32_bf16 v[20:23], v[144:147], v[192:195], v[20:23]
	v_mfma_f32_16x16x32_bf16 v[16:19], v[162:165], v[192:195], v[16:19]
	v_mfma_f32_16x16x32_bf16 v[4:7], v[144:147], v[200:203], v[4:7]
	v_mfma_f32_16x16x32_bf16 v[0:3], v[162:165], v[200:203], v[0:3]
	v_mfma_f32_16x16x32_bf16 v[52:55], v[148:151], v[176:179], v[52:55]
	v_mfma_f32_16x16x32_bf16 v[48:51], v[166:169], v[176:179], v[48:51]
	v_mfma_f32_16x16x32_bf16 v[36:39], v[148:151], v[184:187], v[36:39]
	v_mfma_f32_16x16x32_bf16 v[32:35], v[166:169], v[184:187], v[32:35]
	v_mfma_f32_16x16x32_bf16 v[20:23], v[148:151], v[196:199], v[20:23]
	v_mfma_f32_16x16x32_bf16 v[16:19], v[166:169], v[196:199], v[16:19]
	v_mfma_f32_16x16x32_bf16 v[4:7], v[148:151], v[204:207], v[4:7]
	v_mfma_f32_16x16x32_bf16 v[0:3], v[166:169], v[204:207], v[0:3]
	s_barrier
	s_setprio 0
	s_add_i32 s74, 0, 0x18000
	s_add_i32 s75, 0, 0x1c000
	v_add_u32_e32 v140, s74, v189
	v_add_u32_e32 v166, s75, v189
	ds_read_b128 v[128:131], v140
	ds_read_b128 v[132:135], v140 offset:1024
	ds_read_b128 v[136:139], v140 offset:2048
	ds_read_b128 v[140:143], v140 offset:3072
	ds_read_b128 v[144:147], v166
	ds_read_b128 v[148:151], v166 offset:1024
	ds_read_b128 v[162:165], v166 offset:2048
	ds_read_b128 v[166:169], v166 offset:3072
	s_add_u32 s56, s56, 0x100000
	s_addc_u32 s57, s57, 0
	s_mov_b32 m0, s61
	v_lshl_add_u64 v[224:225], s[56:57], 0, v[156:157]
	ds_read_b128 v[170:173], v191 offset:32768
	ds_read_b128 v[176:179], v191 offset:33792
	ds_read_b128 v[180:183], v191 offset:34816
	ds_read_b128 v[184:187], v191 offset:35840
	ds_read_b128 v[192:195], v191 offset:36864
	ds_read_b128 v[196:199], v191 offset:37888
	ds_read_b128 v[200:203], v191 offset:38912
	ds_read_b128 v[204:207], v191 offset:39936
	global_load_lds_dwordx4 v[224:225], off
	v_lshl_add_u64 v[224:225], s[56:57], 0, v[154:155]
	s_mov_b32 m0, s62
	s_nop 0
	global_load_lds_dwordx4 v[224:225], off
	s_waitcnt vmcnt(8)
	s_waitcnt lgkmcnt(0)
	s_setprio 1
	s_barrier
	v_mfma_f32_16x16x32_bf16 v[124:127], v[128:131], v[170:173], v[124:127]
	v_mfma_f32_16x16x32_bf16 v[120:123], v[136:139], v[170:173], v[120:123]
	v_mfma_f32_16x16x32_bf16 v[108:111], v[128:131], v[180:183], v[108:111]
	v_mfma_f32_16x16x32_bf16 v[104:107], v[136:139], v[180:183], v[104:107]
	v_mfma_f32_16x16x32_bf16 v[92:95], v[128:131], v[192:195], v[92:95]
	v_mfma_f32_16x16x32_bf16 v[88:91], v[136:139], v[192:195], v[88:91]
	v_mfma_f32_16x16x32_bf16 v[76:79], v[128:131], v[200:203], v[76:79]
	v_mfma_f32_16x16x32_bf16 v[72:75], v[136:139], v[200:203], v[72:75]
	v_mfma_f32_16x16x32_bf16 v[124:127], v[132:135], v[176:179], v[124:127]
	v_mfma_f32_16x16x32_bf16 v[120:123], v[140:143], v[176:179], v[120:123]
	v_mfma_f32_16x16x32_bf16 v[108:111], v[132:135], v[184:187], v[108:111]
	v_mfma_f32_16x16x32_bf16 v[104:107], v[140:143], v[184:187], v[104:107]
	v_mfma_f32_16x16x32_bf16 v[92:95], v[132:135], v[196:199], v[92:95]
	v_mfma_f32_16x16x32_bf16 v[88:91], v[140:143], v[196:199], v[88:91]
	v_mfma_f32_16x16x32_bf16 v[76:79], v[132:135], v[204:207], v[76:79]
	v_mfma_f32_16x16x32_bf16 v[72:75], v[140:143], v[204:207], v[72:75]
	v_mfma_f32_16x16x32_bf16 v[116:119], v[144:147], v[170:173], v[116:119]
	v_mfma_f32_16x16x32_bf16 v[112:115], v[162:165], v[170:173], v[112:115]
	v_mfma_f32_16x16x32_bf16 v[100:103], v[144:147], v[180:183], v[100:103]
	v_mfma_f32_16x16x32_bf16 v[96:99], v[162:165], v[180:183], v[96:99]
	v_mfma_f32_16x16x32_bf16 v[84:87], v[144:147], v[192:195], v[84:87]
	v_mfma_f32_16x16x32_bf16 v[80:83], v[162:165], v[192:195], v[80:83]
	v_mfma_f32_16x16x32_bf16 v[68:71], v[144:147], v[200:203], v[68:71]
	v_mfma_f32_16x16x32_bf16 v[64:67], v[162:165], v[200:203], v[64:67]
	v_mfma_f32_16x16x32_bf16 v[116:119], v[148:151], v[176:179], v[116:119]
	v_mfma_f32_16x16x32_bf16 v[112:115], v[166:169], v[176:179], v[112:115]
	v_mfma_f32_16x16x32_bf16 v[100:103], v[148:151], v[184:187], v[100:103]
	v_mfma_f32_16x16x32_bf16 v[96:99], v[166:169], v[184:187], v[96:99]
	v_mfma_f32_16x16x32_bf16 v[84:87], v[148:151], v[196:199], v[84:87]
	v_mfma_f32_16x16x32_bf16 v[80:83], v[166:169], v[196:199], v[80:83]
	v_mfma_f32_16x16x32_bf16 v[68:71], v[148:151], v[204:207], v[68:71]
	v_mfma_f32_16x16x32_bf16 v[64:67], v[166:169], v[204:207], v[64:67]
	s_barrier
; #define PG8_STAGE(bufoff, gbase, voff) do { _Pragma("unroll") for (int _i = 0; _i < 2; ++_i) \
;         __builtin_amdgcn_global_load_lds((const unsigned*)((const char*)(gbase) + (voff)[_i]), (PG8_LAS unsigned*)(lds + (bufoff) + ldsw + _i * 8192), 16, 0, 0); } while (0)
; #define PG8_LDA(dst, b, h) do { _Pragma("unroll") for (int m = 0; m < 4; ++m) _Pragma("unroll") for (int k = 0; k < 2; ++k) dst[m][k] = *(const PG8_LAS bf16x8*)(lds + PG8_SA(b, h) + aoff + m * 2048 + k * 1024); } while (0)
; #define PG8_MMA(ai, bj, At, Bt) do { __builtin_amdgcn_s_setprio(1); _Pragma("unroll") for (int m = 0; m < 4; ++m) _Pragma("unroll") for (int n = 0; n < 2; ++n) _Pragma("unroll") for (int k = 0; k < 2; ++k) \
;         acc[ai][bj][m][n] = __builtin_amdgcn_mfma_f32_16x16x32_bf16(Bt[n][k], At[m][k], acc[ai][bj][m][n], 0, 0, 0); __builtin_amdgcn_s_setprio(0); } while (0)
; #define PG8_WAIT_V(n) asm volatile("s_waitcnt vmcnt(" #n ")" ::: "memory")
; #define PG8_WAIT_L(n) asm volatile("s_waitcnt lgkmcnt(" #n ")" ::: "memory")
; #define PG8_BAR __builtin_amdgcn_s_barrier()
; #define PG8_SCHED __builtin_amdgcn_sched_barrier(0)
;     __device__ __forceinline__ void operator()(const f32x4 (&acc)[2][2][4][2], const Unit& u, int wr, int wc, int fr, int fq, int, PG8_LAS unsigned char*) const {
;     ...
;         for (int ai = 0; ai < 2; ++ai) {
;             u32x4 xw[4][2];
; #pragma unroll
;             for (int m = 0; m < 4; ++m)
; #pragma unroll
;                 for (int bj = 0; bj < 2; ++bj) xw[m][bj] = *(const u32x4*)(xb + (size_t)(row0 + ai * HALF + m * 16) * 1024 + col0 + bj * HALF);
; template <class Epi, class Sched, bool ALIGN_EPI = false, bool SP2 = false>
; __device__ __forceinline__ void gemm_phase(PG8_LAS unsigned char* lds, const Gemm g, const Sched& S, const Epi& E) {
;     ...
;             PG8_LDA(At, 1, 1); PG8_STAGE(PG8_SB(1, 0), b3, voffB); PG8_STAGE(PG8_SB(1, 1), b3 + hstep, voffB); PG8_STAGE(PG8_SA(1, 0), a3, voffA);
;             PG8_WAIT_V(8); PG8_WAIT_L(0); PG8_BAR; PG8_MMA(1, 0, At, B0); PG8_MMA(1, 1, At, B1); PG8_BAR; PG8_SCHED;
	s_setprio 0
	s_add_i32 s56, s74, s58
	v_lshl_add_u64 v[208:209], v[208:209], 0, s[4:5]
	s_mov_b32 m0, s56
	ds_read_b128 v[170:173], v191 offset:49152
	ds_read_b128 v[176:179], v191 offset:50176
	ds_read_b128 v[180:183], v191 offset:51200
	ds_read_b128 v[184:187], v191 offset:52224
	ds_read_b128 v[192:195], v191 offset:53248
	ds_read_b128 v[196:199], v191 offset:54272
	ds_read_b128 v[200:203], v191 offset:55296
	ds_read_b128 v[204:207], v191 offset:56320
	global_load_lds_dwordx4 v[208:209], off
	s_add_i32 m0, s56, 0x2000
	s_add_u32 s54, s54, 0x100080
	v_lshl_add_u64 v[208:209], v[218:219], 0, s[4:5]
	s_addc_u32 s55, s55, 0
	s_add_i32 s56, s75, s58
	global_load_lds_dwordx4 v[208:209], off
	v_lshl_add_u64 v[208:209], s[54:55], 0, v[174:175]
	s_mov_b32 m0, s56
	s_nop 0
	global_load_lds_dwordx4 v[208:209], off
	v_lshl_add_u64 v[208:209], s[54:55], 0, v[152:153]
	s_add_i32 m0, s56, 0x2000
	s_nop 0
	global_load_lds_dwordx4 v[208:209], off
	v_lshl_add_u64 v[208:209], v[220:221], 0, s[4:5]
	s_mov_b32 m0, s64
	s_nop 0
	global_load_lds_dwordx4 v[208:209], off
	v_lshl_add_u64 v[208:209], v[222:223], 0, s[4:5]
	s_mov_b32 m0, s65
	s_nop 0
	global_load_lds_dwordx4 v[208:209], off
	s_waitcnt vmcnt(8)
	s_waitcnt lgkmcnt(0)
	s_setprio 1
	s_barrier
	v_mfma_f32_16x16x32_bf16 v[60:63], v[128:131], v[170:173], v[60:63]
	v_mfma_f32_16x16x32_bf16 v[56:59], v[136:139], v[170:173], v[56:59]
	v_mfma_f32_16x16x32_bf16 v[44:47], v[128:131], v[180:183], v[44:47]
	v_mfma_f32_16x16x32_bf16 v[40:43], v[136:139], v[180:183], v[40:43]
	v_mfma_f32_16x16x32_bf16 v[28:31], v[128:131], v[192:195], v[28:31]
	v_mfma_f32_16x16x32_bf16 v[24:27], v[136:139], v[192:195], v[24:27]
	v_mfma_f32_16x16x32_bf16 v[12:15], v[128:131], v[200:203], v[12:15]
	v_mfma_f32_16x16x32_bf16 v[8:11], v[136:139], v[200:203], v[8:11]
	v_mfma_f32_16x16x32_bf16 v[60:63], v[132:135], v[176:179], v[60:63]
	v_mfma_f32_16x16x32_bf16 v[56:59], v[140:143], v[176:179], v[56:59]
	v_mfma_f32_16x16x32_bf16 v[44:47], v[132:135], v[184:187], v[44:47]
	v_mfma_f32_16x16x32_bf16 v[40:43], v[140:143], v[184:187], v[40:43]
	v_mfma_f32_16x16x32_bf16 v[28:31], v[132:135], v[196:199], v[28:31]
	v_mfma_f32_16x16x32_bf16 v[24:27], v[140:143], v[196:199], v[24:27]
	v_mfma_f32_16x16x32_bf16 v[12:15], v[132:135], v[204:207], v[12:15]
	v_mfma_f32_16x16x32_bf16 v[8:11], v[140:143], v[204:207], v[8:11]
	v_mfma_f32_16x16x32_bf16 v[52:55], v[144:147], v[170:173], v[52:55]
	v_mfma_f32_16x16x32_bf16 v[48:51], v[162:165], v[170:173], v[48:51]
	v_mfma_f32_16x16x32_bf16 v[36:39], v[144:147], v[180:183], v[36:39]
	v_mfma_f32_16x16x32_bf16 v[32:35], v[162:165], v[180:183], v[32:35]
	v_mfma_f32_16x16x32_bf16 v[20:23], v[144:147], v[192:195], v[20:23]
	v_mfma_f32_16x16x32_bf16 v[16:19], v[162:165], v[192:195], v[16:19]
	v_mfma_f32_16x16x32_bf16 v[4:7], v[144:147], v[200:203], v[4:7]
	v_mfma_f32_16x16x32_bf16 v[0:3], v[162:165], v[200:203], v[0:3]
	v_mfma_f32_16x16x32_bf16 v[52:55], v[148:151], v[176:179], v[52:55]
	v_mfma_f32_16x16x32_bf16 v[48:51], v[166:169], v[176:179], v[48:51]
	v_mfma_f32_16x16x32_bf16 v[36:39], v[148:151], v[184:187], v[36:39]
	v_mfma_f32_16x16x32_bf16 v[32:35], v[166:169], v[184:187], v[32:35]
	v_mfma_f32_16x16x32_bf16 v[20:23], v[148:151], v[196:199], v[20:23]
	v_mfma_f32_16x16x32_bf16 v[16:19], v[166:169], v[196:199], v[16:19]
	v_mfma_f32_16x16x32_bf16 v[4:7], v[148:151], v[204:207], v[4:7]
	v_mfma_f32_16x16x32_bf16 v[0:3], v[166:169], v[204:207], v[0:3]
	s_barrier
	s_setprio 0
	s_add_i32 s73, s73, 2
	s_add_u32 s0, s0, 0x100
	s_addc_u32 s1, s1, 0
	s_add_u32 s71, s71, 0x100
	s_addc_u32 s72, s72, 0
	s_cmp_gt_u32 s73, 61
	s_cbranch_scc0 .LBB0_1845
	s_cmp_eq_u64 s[44:45], 0
	s_cbranch_scc1 .Lep4_skip
	s_setprio 1
.Lep4_skip:
.LBB0_1848:
	v_lshl_or_b32 v162, s16, 8, v190
	v_ashrrev_i32_e32 v163, 31, v162
	v_lshl_add_u32 v166, s68, 8, v188
	v_lshlrev_b64 v[128:129], 1, v[162:163]
	v_ashrrev_i32_e32 v167, 31, v166
	v_lshl_add_u64 v[164:165], s[10:11], 0, v[128:129]
	v_lshlrev_b64 v[130:131], 11, v[166:167]
	v_lshl_add_u64 v[132:133], v[164:165], 0, v[130:131]
	global_load_dwordx4 v[176:179], v[132:133], off
	global_load_dwordx4 v[192:195], v[132:133], off offset:256
	v_or_b32_e32 v184, 16, v166
	v_or_b32_e32 v180, 32, v166
	v_or_b32_e32 v168, 48, v166
	v_ashrrev_i32_e32 v185, 31, v184
	v_ashrrev_i32_e32 v181, 31, v180
	v_ashrrev_i32_e32 v169, 31, v168
	v_lshlrev_b64 v[186:187], 11, v[184:185]
	v_lshlrev_b64 v[182:183], 11, v[180:181]
	v_lshlrev_b64 v[170:171], 11, v[168:169]
	v_lshl_add_u64 v[130:131], s[10:11], 0, v[130:131]
	v_lshl_add_u64 v[132:133], v[164:165], 0, v[186:187]
	v_lshl_add_u64 v[134:135], v[164:165], 0, v[182:183]
	v_lshl_add_u64 v[172:173], v[164:165], 0, v[170:171]
	v_lshl_add_u64 v[196:197], v[130:131], 0, v[128:129]
	global_load_dwordx4 v[148:151], v[132:133], off
	global_load_dwordx4 v[144:147], v[132:133], off offset:256
	global_load_dwordx4 v[140:143], v[134:135], off
	global_load_dwordx4 v[136:139], v[134:135], off offset:256
	s_nop 0
	global_load_dwordx4 v[132:135], v[172:173], off
	global_load_dwordx4 v[128:131], v[172:173], off offset:256
	s_lshl_b32 s0, s16, 2
	s_ashr_i32 s1, s0, 31
	s_and_b64 vcc, exec, s[38:39]
	s_cbranch_vccz .Lal4_skip
	s_barrier
